# GEMM K loops (up-proj, in-proj, cross-q, KV): all LDS-DMA source addresses in SGPR-base form; the +K-tile variants use scalar pointers precomputed one super-phase earlier (no VALU address arithmetic l
# speedup vs baseline: 1.0117x; 1.0048x over previous
; #define PG8_STAGE(bufoff, gbase, voff) do { _Pragma("unroll") for (int _i = 0; _i < 2; ++_i) \
;         __builtin_amdgcn_global_load_lds((const unsigned*)((const char*)(gbase) + (voff)[_i]), (PG8_LAS unsigned*)(lds + (bufoff) + ldsw + _i * 8192), 16, 0, 0); } while (0)
; #define PG8_LDA(dst, b, h) do { _Pragma("unroll") for (int m = 0; m < 4; ++m) _Pragma("unroll") for (int k = 0; k < 2; ++k) dst[m][k] = *(const PG8_LAS bf16x8*)(lds + PG8_SA(b, h) + aoff + m * 2048 + k * 1024); } while (0)
; #define PG8_LDB(dst, b, h) do { _Pragma("unroll") for (int n = 0; n < 2; ++n) _Pragma("unroll") for (int k = 0; k < 2; ++k) dst[n][k] = *(const PG8_LAS bf16x8*)(lds + PG8_SB(b, h) + boff + n * 2048 + k * 1024); } while (0)
; #define PG8_WAIT_V(n) asm volatile("s_waitcnt vmcnt(" #n ")" ::: "memory")
; #define PG8_WAIT_L(n) asm volatile("s_waitcnt lgkmcnt(" #n ")" ::: "memory")
; #define PG8_BAR __builtin_amdgcn_s_barrier()
; #define PG8_SCHED __builtin_amdgcn_sched_barrier(0)
; template <class Epi, class Sched, bool ALIGN_EPI = false, bool SP2 = false>
; __device__ __forceinline__ void gemm_phase(PG8_LAS unsigned char* lds, const Gemm g, const Sched& S, const Epi& E) {
;     ...
;         const bool has_next = S.next(ui + 1, nxt);
;         const char* nA = has_next ? (const char*)g.A + (size_t)nxt.pm * tstep : cA; const char* nB = has_next ? (const char*)g.Bt + (size_t)nxt.pn * tstep : cB;
;         for (int t = 0; t < nt; t += 2) {
;             const bool last = (t == nt - 2);
;             const char* a1 = cA + (size_t)(t + 1) * kstep;
;             const char* a2 = last ? nA : cA + (size_t)(t + 2) * kstep; const char* b2 = last ? nB : cB + (size_t)(t + 2) * kstep;
;             const char* a3 = a2 + kstep; const char* b3 = b2 + kstep;
;             if (last && has_next) S.a_ready(nxt);
;             if constexpr (SP2) {
;             PG8_LDB(B0, 0, 0); PG8_LDB(B1, 0, 1); PG8_SCHED; PG8_LDA(At, 0, 0); PG8_STAGE(PG8_SA(1, 1), a1 + hstep, voffA);
;             PG8_WAIT_V(8); PG8_WAIT_L(0); PG8_BAR; PG8_MMA(0, 0, At, B0); PG8_MMA(0, 1, At, B1); PG8_BAR; PG8_SCHED;
;             PG8_LDA(At, 0, 1); PG8_STAGE(PG8_SB(0, 0), b2, voffB); PG8_STAGE(PG8_SB(0, 1), b2 + hstep, voffB); PG8_STAGE(PG8_SA(0, 0), a2, voffA);
;             PG8_WAIT_V(8); PG8_WAIT_L(0); PG8_BAR; PG8_MMA(1, 0, At, B0); PG8_MMA(1, 1, At, B1); PG8_BAR; PG8_SCHED;
.LBB0_38:
	s_add_u32 s10, vcc_lo, 0xfff80080
	s_addc_u32 s11, vcc_hi, -1
	s_add_i32 s84, 0, 0x10000
	s_cmp_eq_u32 s13, 28
	s_cselect_b32 s69, s27, s11
	s_cselect_b32 s68, s86, s10
	s_cselect_b32 s11, s17, s12
	s_cselect_b32 s10, s88, s21
	s_add_i32 s93, 0, 0x14000
	v_add_u32_e32 v138, s84, v194
	v_add_u32_e32 v164, s93, v194
	ds_read_b128 v[114:117], v138
	ds_read_b128 v[118:121], v138 offset:1024
	ds_read_b128 v[130:133], v138 offset:2048
	ds_read_b128 v[138:141], v138 offset:3072
	ds_read_b128 v[146:149], v164
	ds_read_b128 v[156:159], v164 offset:1024
	ds_read_b128 v[160:163], v164 offset:2048
	ds_read_b128 v[164:167], v164 offset:3072
	s_add_i32 m0, s2, 0xc000
	ds_read_b128 v[168:171], v199
	ds_read_b128 v[172:175], v199 offset:1024
	ds_read_b128 v[176:179], v199 offset:2048
	ds_read_b128 v[180:183], v199 offset:3072
	ds_read_b128 v[184:187], v199 offset:4096
	ds_read_b128 v[188:191], v199 offset:5120
	ds_read_b128 v[200:203], v199 offset:6144
	ds_read_b128 v[204:207], v199 offset:7168
	global_load_lds_dwordx4 v152, vcc
	s_add_i32 m0, s2, 0xe000
	s_nop 0
	global_load_lds_dwordx4 v154, vcc
	s_waitcnt vmcnt(8)
	s_waitcnt lgkmcnt(0)
	s_setprio 1
	s_barrier
	v_mfma_f32_16x16x32_bf16 v[142:145], v[114:117], v[168:171], v[142:145]
	v_mfma_f32_16x16x32_bf16 v[62:65], v[130:133], v[168:171], v[62:65]
	v_mfma_f32_16x16x32_bf16 v[122:125], v[114:117], v[176:179], v[122:125]
	v_mfma_f32_16x16x32_bf16 v[50:53], v[130:133], v[176:179], v[50:53]
	v_mfma_f32_16x16x32_bf16 v[106:109], v[114:117], v[184:187], v[106:109]
	v_mfma_f32_16x16x32_bf16 v[42:45], v[130:133], v[184:187], v[42:45]
	v_mfma_f32_16x16x32_bf16 v[98:101], v[114:117], v[200:203], v[98:101]
	v_mfma_f32_16x16x32_bf16 v[34:37], v[130:133], v[200:203], v[34:37]
	v_mfma_f32_16x16x32_bf16 v[142:145], v[118:121], v[172:175], v[142:145]
	v_mfma_f32_16x16x32_bf16 v[62:65], v[138:141], v[172:175], v[62:65]
	v_mfma_f32_16x16x32_bf16 v[122:125], v[118:121], v[180:183], v[122:125]
	v_mfma_f32_16x16x32_bf16 v[50:53], v[138:141], v[180:183], v[50:53]
	v_mfma_f32_16x16x32_bf16 v[106:109], v[118:121], v[188:191], v[106:109]
	v_mfma_f32_16x16x32_bf16 v[42:45], v[138:141], v[188:191], v[42:45]
	v_mfma_f32_16x16x32_bf16 v[98:101], v[118:121], v[204:207], v[98:101]
	v_mfma_f32_16x16x32_bf16 v[34:37], v[138:141], v[204:207], v[34:37]
	v_mfma_f32_16x16x32_bf16 v[134:137], v[146:149], v[168:171], v[134:137]
	v_mfma_f32_16x16x32_bf16 v[58:61], v[160:163], v[168:171], v[58:61]
	v_mfma_f32_16x16x32_bf16 v[126:129], v[146:149], v[176:179], v[126:129]
	v_mfma_f32_16x16x32_bf16 v[54:57], v[160:163], v[176:179], v[54:57]
	v_mfma_f32_16x16x32_bf16 v[110:113], v[146:149], v[184:187], v[110:113]
	v_mfma_f32_16x16x32_bf16 v[46:49], v[160:163], v[184:187], v[46:49]
	v_mfma_f32_16x16x32_bf16 v[102:105], v[146:149], v[200:203], v[102:105]
	v_mfma_f32_16x16x32_bf16 v[38:41], v[160:163], v[200:203], v[38:41]
	v_mfma_f32_16x16x32_bf16 v[134:137], v[156:159], v[172:175], v[134:137]
	v_mfma_f32_16x16x32_bf16 v[58:61], v[164:167], v[172:175], v[58:61]
	v_mfma_f32_16x16x32_bf16 v[126:129], v[156:159], v[180:183], v[126:129]
	v_mfma_f32_16x16x32_bf16 v[54:57], v[164:167], v[180:183], v[54:57]
	v_mfma_f32_16x16x32_bf16 v[110:113], v[156:159], v[188:191], v[110:113]
	v_mfma_f32_16x16x32_bf16 v[46:49], v[164:167], v[188:191], v[46:49]
	v_mfma_f32_16x16x32_bf16 v[102:105], v[156:159], v[204:207], v[102:105]
	v_mfma_f32_16x16x32_bf16 v[38:41], v[164:167], v[204:207], v[38:41]
	s_barrier
	s_setprio 0
	s_add_i32 s84, s84, s1
	s_add_u32 s100, s10, 0x80
	s_addc_u32 s101, s11, 0
	s_mov_b32 m0, s84
	ds_read_b128 v[168:171], v199 offset:16384
	ds_read_b128 v[172:175], v199 offset:17408
	ds_read_b128 v[176:179], v199 offset:18432
	ds_read_b128 v[180:183], v199 offset:19456
	ds_read_b128 v[184:187], v199 offset:20480
	ds_read_b128 v[188:191], v199 offset:21504
	ds_read_b128 v[200:203], v199 offset:22528
	ds_read_b128 v[204:207], v199 offset:23552
	global_load_lds_dwordx4 v0, s[10:11]
	s_add_i32 m0, s84, 0x2000
	s_add_u32 s84, s10, 0x80000
	s_addc_u32 s85, s11, 0
	s_add_i32 s93, s93, s1
	global_load_lds_dwordx4 v150, s[10:11]
	s_mov_b32 m0, s93
	s_add_u32 s98, s68, 0x80
	s_addc_u32 s99, s69, 0
	global_load_lds_dwordx4 v0, s[84:85]
	s_add_i32 m0, s93, 0x2000
	s_nop 0
	global_load_lds_dwordx4 v150, s[84:85]
	s_mov_b32 m0, s2
	s_nop 0
	global_load_lds_dwordx4 v0, s[68:69]
	s_mov_b32 m0, s4
	s_nop 0
	global_load_lds_dwordx4 v150, s[68:69]
	s_waitcnt vmcnt(8)
	s_waitcnt lgkmcnt(0)
	s_setprio 1
	s_barrier
	v_mfma_f32_16x16x32_bf16 v[94:97], v[114:117], v[168:171], v[94:97]
	v_mfma_f32_16x16x32_bf16 v[30:33], v[130:133], v[168:171], v[30:33]
	v_mfma_f32_16x16x32_bf16 v[82:85], v[114:117], v[176:179], v[82:85]
	v_mfma_f32_16x16x32_bf16 v[18:21], v[130:133], v[176:179], v[18:21]
	v_mfma_f32_16x16x32_bf16 v[74:77], v[114:117], v[184:187], v[74:77]
	v_mfma_f32_16x16x32_bf16 v[10:13], v[130:133], v[184:187], v[10:13]
	v_mfma_f32_16x16x32_bf16 v[66:69], v[114:117], v[200:203], v[66:69]
	v_mfma_f32_16x16x32_bf16 v[2:5], v[130:133], v[200:203], v[2:5]
	v_mfma_f32_16x16x32_bf16 v[94:97], v[118:121], v[172:175], v[94:97]
	v_mfma_f32_16x16x32_bf16 v[30:33], v[138:141], v[172:175], v[30:33]
	v_mfma_f32_16x16x32_bf16 v[82:85], v[118:121], v[180:183], v[82:85]
	v_mfma_f32_16x16x32_bf16 v[18:21], v[138:141], v[180:183], v[18:21]
	v_mfma_f32_16x16x32_bf16 v[74:77], v[118:121], v[188:191], v[74:77]
	v_mfma_f32_16x16x32_bf16 v[10:13], v[138:141], v[188:191], v[10:13]
	v_mfma_f32_16x16x32_bf16 v[66:69], v[118:121], v[204:207], v[66:69]
	v_mfma_f32_16x16x32_bf16 v[2:5], v[138:141], v[204:207], v[2:5]
	v_mfma_f32_16x16x32_bf16 v[90:93], v[146:149], v[168:171], v[90:93]
	v_mfma_f32_16x16x32_bf16 v[26:29], v[160:163], v[168:171], v[26:29]
	v_mfma_f32_16x16x32_bf16 v[86:89], v[146:149], v[176:179], v[86:89]
	v_mfma_f32_16x16x32_bf16 v[22:25], v[160:163], v[176:179], v[22:25]
	v_mfma_f32_16x16x32_bf16 v[78:81], v[146:149], v[184:187], v[78:81]
	v_mfma_f32_16x16x32_bf16 v[14:17], v[160:163], v[184:187], v[14:17]
	v_mfma_f32_16x16x32_bf16 v[70:73], v[146:149], v[200:203], v[70:73]
	v_mfma_f32_16x16x32_bf16 v[6:9], v[160:163], v[200:203], v[6:9]
	v_mfma_f32_16x16x32_bf16 v[90:93], v[156:159], v[172:175], v[90:93]
	v_mfma_f32_16x16x32_bf16 v[26:29], v[164:167], v[172:175], v[26:29]
	v_mfma_f32_16x16x32_bf16 v[86:89], v[156:159], v[180:183], v[86:89]
	v_mfma_f32_16x16x32_bf16 v[22:25], v[164:167], v[180:183], v[22:25]
	v_mfma_f32_16x16x32_bf16 v[78:81], v[156:159], v[188:191], v[78:81]
	v_mfma_f32_16x16x32_bf16 v[14:17], v[164:167], v[188:191], v[14:17]
	v_mfma_f32_16x16x32_bf16 v[70:73], v[156:159], v[204:207], v[70:73]
	v_mfma_f32_16x16x32_bf16 v[6:9], v[164:167], v[204:207], v[6:9]
	s_barrier
; #define PG8_STAGE(bufoff, gbase, voff) do { _Pragma("unroll") for (int _i = 0; _i < 2; ++_i) \
;         __builtin_amdgcn_global_load_lds((const unsigned*)((const char*)(gbase) + (voff)[_i]), (PG8_LAS unsigned*)(lds + (bufoff) + ldsw + _i * 8192), 16, 0, 0); } while (0)
; #define PG8_LDA(dst, b, h) do { _Pragma("unroll") for (int m = 0; m < 4; ++m) _Pragma("unroll") for (int k = 0; k < 2; ++k) dst[m][k] = *(const PG8_LAS bf16x8*)(lds + PG8_SA(b, h) + aoff + m * 2048 + k * 1024); } while (0)
; #define PG8_LDB(dst, b, h) do { _Pragma("unroll") for (int n = 0; n < 2; ++n) _Pragma("unroll") for (int k = 0; k < 2; ++k) dst[n][k] = *(const PG8_LAS bf16x8*)(lds + PG8_SB(b, h) + boff + n * 2048 + k * 1024); } while (0)
; #define PG8_MMA(ai, bj, At, Bt) do { __builtin_amdgcn_s_setprio(1); _Pragma("unroll") for (int m = 0; m < 4; ++m) _Pragma("unroll") for (int n = 0; n < 2; ++n) _Pragma("unroll") for (int k = 0; k < 2; ++k) \
;         acc[ai][bj][m][n] = __builtin_amdgcn_mfma_f32_16x16x32_bf16(Bt[n][k], At[m][k], acc[ai][bj][m][n], 0, 0, 0); __builtin_amdgcn_s_setprio(0); } while (0)
; #define PG8_WAIT_V(n) asm volatile("s_waitcnt vmcnt(" #n ")" ::: "memory")
; #define PG8_WAIT_L(n) asm volatile("s_waitcnt lgkmcnt(" #n ")" ::: "memory")
; #define PG8_BAR __builtin_amdgcn_s_barrier()
; #define PG8_SCHED __builtin_amdgcn_sched_barrier(0)
; template <class Epi, class Sched, bool ALIGN_EPI = false, bool SP2 = false>
; __device__ __forceinline__ void gemm_phase(PG8_LAS unsigned char* lds, const Gemm g, const Sched& S, const Epi& E) {
;     ...
;             PG8_WAIT_V(8); PG8_WAIT_L(0); PG8_BAR; PG8_MMA(1, 0, At, B0); PG8_MMA(1, 1, At, B1); PG8_BAR; PG8_SCHED;
;             PG8_LDB(B0, 1, 0); PG8_LDB(B1, 1, 1); PG8_SCHED; PG8_LDA(At, 1, 0); PG8_STAGE(PG8_SA(0, 1), a2 + hstep, voffA);
;             PG8_WAIT_V(8); PG8_WAIT_L(0); PG8_BAR; PG8_MMA(0, 0, At, B0); PG8_MMA(0, 1, At, B1); PG8_BAR; PG8_SCHED;
;             PG8_LDA(At, 1, 1); PG8_STAGE(PG8_SB(1, 0), b3, voffB); PG8_STAGE(PG8_SB(1, 1), b3 + hstep, voffB); PG8_STAGE(PG8_SA(1, 0), a3, voffA);
;             PG8_WAIT_V(8); PG8_WAIT_L(0); PG8_BAR; PG8_MMA(1, 0, At, B0); PG8_MMA(1, 1, At, B1); PG8_BAR; PG8_SCHED;
	s_setprio 0
	s_add_i32 s84, 0, 0x18000
	s_add_i32 s85, 0, 0x1c000
	v_add_u32_e32 v138, s84, v194
	v_add_u32_e32 v164, s85, v194
	ds_read_b128 v[114:117], v138
	ds_read_b128 v[118:121], v138 offset:1024
	ds_read_b128 v[130:133], v138 offset:2048
	ds_read_b128 v[138:141], v138 offset:3072
	ds_read_b128 v[146:149], v164
	ds_read_b128 v[156:159], v164 offset:1024
	ds_read_b128 v[160:163], v164 offset:2048
	ds_read_b128 v[164:167], v164 offset:3072
	s_add_u32 s68, s68, 0x80000
	s_addc_u32 s69, s69, 0
	s_mov_b32 m0, s5
	ds_read_b128 v[168:171], v199 offset:32768
	ds_read_b128 v[172:175], v199 offset:33792
	ds_read_b128 v[176:179], v199 offset:34816
	ds_read_b128 v[180:183], v199 offset:35840
	ds_read_b128 v[184:187], v199 offset:36864
	ds_read_b128 v[188:191], v199 offset:37888
	ds_read_b128 v[200:203], v199 offset:38912
	ds_read_b128 v[204:207], v199 offset:39936
	global_load_lds_dwordx4 v0, s[68:69]
	s_mov_b32 m0, s6
	s_nop 0
	global_load_lds_dwordx4 v150, s[68:69]
	s_waitcnt vmcnt(8)
	s_waitcnt lgkmcnt(0)
	s_setprio 1
	s_barrier
	v_mfma_f32_16x16x32_bf16 v[142:145], v[114:117], v[168:171], v[142:145]
	v_mfma_f32_16x16x32_bf16 v[62:65], v[130:133], v[168:171], v[62:65]
	v_mfma_f32_16x16x32_bf16 v[122:125], v[114:117], v[176:179], v[122:125]
	v_mfma_f32_16x16x32_bf16 v[50:53], v[130:133], v[176:179], v[50:53]
	v_mfma_f32_16x16x32_bf16 v[106:109], v[114:117], v[184:187], v[106:109]
	v_mfma_f32_16x16x32_bf16 v[42:45], v[130:133], v[184:187], v[42:45]
	v_mfma_f32_16x16x32_bf16 v[98:101], v[114:117], v[200:203], v[98:101]
	v_mfma_f32_16x16x32_bf16 v[34:37], v[130:133], v[200:203], v[34:37]
	v_mfma_f32_16x16x32_bf16 v[142:145], v[118:121], v[172:175], v[142:145]
	v_mfma_f32_16x16x32_bf16 v[62:65], v[138:141], v[172:175], v[62:65]
	v_mfma_f32_16x16x32_bf16 v[122:125], v[118:121], v[180:183], v[122:125]
	v_mfma_f32_16x16x32_bf16 v[50:53], v[138:141], v[180:183], v[50:53]
	v_mfma_f32_16x16x32_bf16 v[106:109], v[118:121], v[188:191], v[106:109]
	v_mfma_f32_16x16x32_bf16 v[42:45], v[138:141], v[188:191], v[42:45]
	v_mfma_f32_16x16x32_bf16 v[98:101], v[118:121], v[204:207], v[98:101]
	v_mfma_f32_16x16x32_bf16 v[34:37], v[138:141], v[204:207], v[34:37]
	v_mfma_f32_16x16x32_bf16 v[134:137], v[146:149], v[168:171], v[134:137]
	v_mfma_f32_16x16x32_bf16 v[58:61], v[160:163], v[168:171], v[58:61]
	v_mfma_f32_16x16x32_bf16 v[126:129], v[146:149], v[176:179], v[126:129]
	v_mfma_f32_16x16x32_bf16 v[54:57], v[160:163], v[176:179], v[54:57]
	v_mfma_f32_16x16x32_bf16 v[110:113], v[146:149], v[184:187], v[110:113]
	v_mfma_f32_16x16x32_bf16 v[46:49], v[160:163], v[184:187], v[46:49]
	v_mfma_f32_16x16x32_bf16 v[102:105], v[146:149], v[200:203], v[102:105]
	v_mfma_f32_16x16x32_bf16 v[38:41], v[160:163], v[200:203], v[38:41]
	v_mfma_f32_16x16x32_bf16 v[134:137], v[156:159], v[172:175], v[134:137]
	v_mfma_f32_16x16x32_bf16 v[58:61], v[164:167], v[172:175], v[58:61]
	v_mfma_f32_16x16x32_bf16 v[126:129], v[156:159], v[180:183], v[126:129]
	v_mfma_f32_16x16x32_bf16 v[54:57], v[164:167], v[180:183], v[54:57]
	v_mfma_f32_16x16x32_bf16 v[110:113], v[156:159], v[188:191], v[110:113]
	v_mfma_f32_16x16x32_bf16 v[46:49], v[164:167], v[188:191], v[46:49]
	v_mfma_f32_16x16x32_bf16 v[102:105], v[156:159], v[204:207], v[102:105]
	v_mfma_f32_16x16x32_bf16 v[38:41], v[164:167], v[204:207], v[38:41]
	s_barrier
	s_setprio 0
	s_add_i32 s68, s84, s1
	s_mov_b32 m0, s68
	ds_read_b128 v[168:171], v199 offset:49152
	ds_read_b128 v[172:175], v199 offset:50176
	ds_read_b128 v[176:179], v199 offset:51200
	ds_read_b128 v[180:183], v199 offset:52224
	ds_read_b128 v[184:187], v199 offset:53248
	ds_read_b128 v[188:191], v199 offset:54272
	ds_read_b128 v[200:203], v199 offset:55296
	ds_read_b128 v[204:207], v199 offset:56320
	global_load_lds_dwordx4 v0, s[100:101]
	s_add_i32 m0, s68, 0x2000
	s_add_i32 s68, s85, s1
	global_load_lds_dwordx4 v150, s[100:101]
	s_add_u32 s10, s10, 0x80080
	s_addc_u32 s11, s11, 0
	s_mov_b32 m0, s68
	s_nop 0
	global_load_lds_dwordx4 v0, s[10:11]
	s_add_i32 m0, s68, 0x2000
	s_nop 0
	global_load_lds_dwordx4 v150, s[10:11]
	s_mov_b32 m0, s7
	s_nop 0
	global_load_lds_dwordx4 v0, s[98:99]
	s_mov_b32 m0, s30
	s_nop 0
	global_load_lds_dwordx4 v150, s[98:99]
	s_waitcnt vmcnt(8)
	s_waitcnt lgkmcnt(0)
	s_setprio 1
	s_barrier
	v_mfma_f32_16x16x32_bf16 v[94:97], v[114:117], v[168:171], v[94:97]
	v_mfma_f32_16x16x32_bf16 v[30:33], v[130:133], v[168:171], v[30:33]
	v_mfma_f32_16x16x32_bf16 v[82:85], v[114:117], v[176:179], v[82:85]
	v_mfma_f32_16x16x32_bf16 v[18:21], v[130:133], v[176:179], v[18:21]
	v_mfma_f32_16x16x32_bf16 v[74:77], v[114:117], v[184:187], v[74:77]
	v_mfma_f32_16x16x32_bf16 v[10:13], v[130:133], v[184:187], v[10:13]
	v_mfma_f32_16x16x32_bf16 v[66:69], v[114:117], v[200:203], v[66:69]
	v_mfma_f32_16x16x32_bf16 v[2:5], v[130:133], v[200:203], v[2:5]
	v_mfma_f32_16x16x32_bf16 v[94:97], v[118:121], v[172:175], v[94:97]
	v_mfma_f32_16x16x32_bf16 v[30:33], v[138:141], v[172:175], v[30:33]
	v_mfma_f32_16x16x32_bf16 v[82:85], v[118:121], v[180:183], v[82:85]
	v_mfma_f32_16x16x32_bf16 v[18:21], v[138:141], v[180:183], v[18:21]
	v_mfma_f32_16x16x32_bf16 v[74:77], v[118:121], v[188:191], v[74:77]
	v_mfma_f32_16x16x32_bf16 v[10:13], v[138:141], v[188:191], v[10:13]
	v_mfma_f32_16x16x32_bf16 v[66:69], v[118:121], v[204:207], v[66:69]
	v_mfma_f32_16x16x32_bf16 v[2:5], v[138:141], v[204:207], v[2:5]
	v_mfma_f32_16x16x32_bf16 v[90:93], v[146:149], v[168:171], v[90:93]
	v_mfma_f32_16x16x32_bf16 v[26:29], v[160:163], v[168:171], v[26:29]
	v_mfma_f32_16x16x32_bf16 v[86:89], v[146:149], v[176:179], v[86:89]
	v_mfma_f32_16x16x32_bf16 v[22:25], v[160:163], v[176:179], v[22:25]
	v_mfma_f32_16x16x32_bf16 v[78:81], v[146:149], v[184:187], v[78:81]
	v_mfma_f32_16x16x32_bf16 v[14:17], v[160:163], v[184:187], v[14:17]
	v_mfma_f32_16x16x32_bf16 v[70:73], v[146:149], v[200:203], v[70:73]
	v_mfma_f32_16x16x32_bf16 v[6:9], v[160:163], v[200:203], v[6:9]
	v_mfma_f32_16x16x32_bf16 v[90:93], v[156:159], v[172:175], v[90:93]
	v_mfma_f32_16x16x32_bf16 v[26:29], v[164:167], v[172:175], v[26:29]
	v_mfma_f32_16x16x32_bf16 v[86:89], v[156:159], v[180:183], v[86:89]
	v_mfma_f32_16x16x32_bf16 v[22:25], v[164:167], v[180:183], v[22:25]
	v_mfma_f32_16x16x32_bf16 v[78:81], v[156:159], v[188:191], v[78:81]
	v_mfma_f32_16x16x32_bf16 v[14:17], v[164:167], v[188:191], v[14:17]
	v_mfma_f32_16x16x32_bf16 v[70:73], v[156:159], v[204:207], v[70:73]
	v_mfma_f32_16x16x32_bf16 v[6:9], v[164:167], v[204:207], v[6:9]
	s_barrier
	s_setprio 0
	s_add_i32 s13, s13, 2
	s_add_u32 vcc_lo, vcc_lo, 0x100
	s_addc_u32 vcc_hi, vcc_hi, 0
	s_add_u32 s21, s21, 0x100
	s_addc_u32 s12, s12, 0
	s_cmp_gt_u32 s13, 29
	s_cbranch_scc0 .LBB0_38
	s_and_b64 vcc, exec, s[58:59]
	s_cbranch_vccz .LBB0_41
	s_barrier

; #define PG8_STAGE(bufoff, gbase, voff) do { _Pragma("unroll") for (int _i = 0; _i < 2; ++_i) \
;         __builtin_amdgcn_global_load_lds((const unsigned*)((const char*)(gbase) + (voff)[_i]), (PG8_LAS unsigned*)(lds + (bufoff) + ldsw + _i * 8192), 16, 0, 0); } while (0)
; #define PG8_LDA(dst, b, h) do { _Pragma("unroll") for (int m = 0; m < 4; ++m) _Pragma("unroll") for (int k = 0; k < 2; ++k) dst[m][k] = *(const PG8_LAS bf16x8*)(lds + PG8_SA(b, h) + aoff + m * 2048 + k * 1024); } while (0)
; #define PG8_LDB(dst, b, h) do { _Pragma("unroll") for (int n = 0; n < 2; ++n) _Pragma("unroll") for (int k = 0; k < 2; ++k) dst[n][k] = *(const PG8_LAS bf16x8*)(lds + PG8_SB(b, h) + boff + n * 2048 + k * 1024); } while (0)
; #define PG8_WAIT_V(n) asm volatile("s_waitcnt vmcnt(" #n ")" ::: "memory")
; #define PG8_WAIT_L(n) asm volatile("s_waitcnt lgkmcnt(" #n ")" ::: "memory")
; #define PG8_BAR __builtin_amdgcn_s_barrier()
; #define PG8_SCHED __builtin_amdgcn_sched_barrier(0)
; template <class Epi, class Sched, bool ALIGN_EPI = false, bool SP2 = false>
; __device__ __forceinline__ void gemm_phase(PG8_LAS unsigned char* lds, const Gemm g, const Sched& S, const Epi& E) {
;     ...
;         const bool has_next = S.next(ui + 1, nxt);
;         const char* nA = has_next ? (const char*)g.A + (size_t)nxt.pm * tstep : cA; const char* nB = has_next ? (const char*)g.Bt + (size_t)nxt.pn * tstep : cB;
;         for (int t = 0; t < nt; t += 2) {
;             const bool last = (t == nt - 2);
;             const char* a1 = cA + (size_t)(t + 1) * kstep;
;             const char* a2 = last ? nA : cA + (size_t)(t + 2) * kstep; const char* b2 = last ? nB : cB + (size_t)(t + 2) * kstep;
;             const char* a3 = a2 + kstep; const char* b3 = b2 + kstep;
;             if (last && has_next) S.a_ready(nxt);
;             if constexpr (SP2) {
;             PG8_LDB(B0, 0, 0); PG8_LDB(B1, 0, 1); PG8_SCHED; PG8_LDA(At, 0, 0); PG8_STAGE(PG8_SA(1, 1), a1 + hstep, voffA);
;             PG8_WAIT_V(8); PG8_WAIT_L(0); PG8_BAR; PG8_MMA(0, 0, At, B0); PG8_MMA(0, 1, At, B1); PG8_BAR; PG8_SCHED;
;             PG8_LDA(At, 0, 1); PG8_STAGE(PG8_SB(0, 0), b2, voffB); PG8_STAGE(PG8_SB(0, 1), b2 + hstep, voffB); PG8_STAGE(PG8_SA(0, 0), a2, voffA);
;             PG8_WAIT_V(8); PG8_WAIT_L(0); PG8_BAR; PG8_MMA(1, 0, At, B0); PG8_MMA(1, 1, At, B1); PG8_BAR; PG8_SCHED;
.LBB0_169:
	s_add_u32 s10, s16, 0xfff80080
	s_addc_u32 s11, s17, -1
	s_add_i32 s21, 0, 0x10000
	s_cmp_eq_u32 s13, 28
	s_cselect_b32 s57, s43, s11
	s_cselect_b32 s56, s47, s10
	v_add_u32_e32 v148, s21, v151
	s_cselect_b32 s11, s45, s12
	s_cselect_b32 s10, s60, s61
	s_add_i32 s64, 0, 0x14000
	ds_read_b128 v[140:143], v148
	ds_read_b128 v[144:147], v148 offset:1024
	ds_read_b128 v[154:157], v148 offset:2048
	ds_read_b128 v[158:161], v148 offset:3072
	v_add_u32_e32 v148, s64, v151
	ds_read_b128 v[162:165], v148
	ds_read_b128 v[166:169], v148 offset:1024
	ds_read_b128 v[170:173], v148 offset:2048
	ds_read_b128 v[174:177], v148 offset:3072
	s_add_i32 m0, s2, 0xc000
	ds_read_b128 v[178:181], v153
	ds_read_b128 v[182:185], v153 offset:1024
	ds_read_b128 v[186:189], v153 offset:2048
	ds_read_b128 v[190:193], v153 offset:3072
	ds_read_b128 v[194:197], v153 offset:4096
	ds_read_b128 v[198:201], v153 offset:5120
	ds_read_b128 v[202:205], v153 offset:6144
	ds_read_b128 v[206:209], v153 offset:7168
	global_load_lds_dwordx4 v136, s[16:17]
	s_add_i32 m0, s2, 0xe000
	s_nop 0
	global_load_lds_dwordx4 v138, s[16:17]
	s_waitcnt vmcnt(8)
	s_waitcnt lgkmcnt(0)
	s_setprio 1
	s_barrier
	v_mfma_f32_16x16x32_bf16 v[126:129], v[140:143], v[178:181], v[126:129]
	v_mfma_f32_16x16x32_bf16 v[122:125], v[154:157], v[178:181], v[122:125]
	v_mfma_f32_16x16x32_bf16 v[110:113], v[140:143], v[186:189], v[110:113]
	v_mfma_f32_16x16x32_bf16 v[106:109], v[154:157], v[186:189], v[106:109]
	v_mfma_f32_16x16x32_bf16 v[94:97], v[140:143], v[194:197], v[94:97]
	v_mfma_f32_16x16x32_bf16 v[90:93], v[154:157], v[194:197], v[90:93]
	v_mfma_f32_16x16x32_bf16 v[78:81], v[140:143], v[202:205], v[78:81]
	v_mfma_f32_16x16x32_bf16 v[74:77], v[154:157], v[202:205], v[74:77]
	v_mfma_f32_16x16x32_bf16 v[126:129], v[144:147], v[182:185], v[126:129]
	v_mfma_f32_16x16x32_bf16 v[122:125], v[158:161], v[182:185], v[122:125]
	v_mfma_f32_16x16x32_bf16 v[110:113], v[144:147], v[190:193], v[110:113]
	v_mfma_f32_16x16x32_bf16 v[106:109], v[158:161], v[190:193], v[106:109]
	v_mfma_f32_16x16x32_bf16 v[94:97], v[144:147], v[198:201], v[94:97]
	v_mfma_f32_16x16x32_bf16 v[90:93], v[158:161], v[198:201], v[90:93]
	v_mfma_f32_16x16x32_bf16 v[78:81], v[144:147], v[206:209], v[78:81]
	v_mfma_f32_16x16x32_bf16 v[74:77], v[158:161], v[206:209], v[74:77]
	v_mfma_f32_16x16x32_bf16 v[118:121], v[162:165], v[178:181], v[118:121]
	v_mfma_f32_16x16x32_bf16 v[114:117], v[170:173], v[178:181], v[114:117]
	v_mfma_f32_16x16x32_bf16 v[102:105], v[162:165], v[186:189], v[102:105]
	v_mfma_f32_16x16x32_bf16 v[98:101], v[170:173], v[186:189], v[98:101]
	v_mfma_f32_16x16x32_bf16 v[86:89], v[162:165], v[194:197], v[86:89]
	v_mfma_f32_16x16x32_bf16 v[82:85], v[170:173], v[194:197], v[82:85]
	v_mfma_f32_16x16x32_bf16 v[70:73], v[162:165], v[202:205], v[70:73]
	v_mfma_f32_16x16x32_bf16 v[66:69], v[170:173], v[202:205], v[66:69]
	v_mfma_f32_16x16x32_bf16 v[118:121], v[166:169], v[182:185], v[118:121]
	v_mfma_f32_16x16x32_bf16 v[114:117], v[174:177], v[182:185], v[114:117]
	v_mfma_f32_16x16x32_bf16 v[102:105], v[166:169], v[190:193], v[102:105]
	v_mfma_f32_16x16x32_bf16 v[98:101], v[174:177], v[190:193], v[98:101]
	v_mfma_f32_16x16x32_bf16 v[86:89], v[166:169], v[198:201], v[86:89]
	v_mfma_f32_16x16x32_bf16 v[82:85], v[174:177], v[198:201], v[82:85]
	v_mfma_f32_16x16x32_bf16 v[70:73], v[166:169], v[206:209], v[70:73]
	v_mfma_f32_16x16x32_bf16 v[66:69], v[174:177], v[206:209], v[66:69]
	s_barrier
	s_setprio 0
	s_add_i32 s21, s21, s1
	s_add_u32 s100, s10, 0x80
	s_addc_u32 s101, s11, 0
	s_mov_b32 m0, s21
	ds_read_b128 v[178:181], v153 offset:16384
	ds_read_b128 v[182:185], v153 offset:17408
	ds_read_b128 v[186:189], v153 offset:18432
	ds_read_b128 v[190:193], v153 offset:19456
	ds_read_b128 v[194:197], v153 offset:20480
	ds_read_b128 v[198:201], v153 offset:21504
	ds_read_b128 v[202:205], v153 offset:22528
	ds_read_b128 v[206:209], v153 offset:23552
	global_load_lds_dwordx4 v0, s[10:11]
	s_add_i32 m0, s21, 0x2000
	s_add_u32 s62, s10, 0x80000
	s_addc_u32 s63, s11, 0
	s_add_i32 s21, s64, s1
	global_load_lds_dwordx4 v134, s[10:11]
	s_mov_b32 m0, s21
	s_add_u32 s98, s56, 0x80
	s_addc_u32 s99, s57, 0
	global_load_lds_dwordx4 v0, s[62:63]
	s_add_i32 m0, s21, 0x2000
	s_nop 0
	global_load_lds_dwordx4 v134, s[62:63]
	s_mov_b32 m0, s2
	s_nop 0
	global_load_lds_dwordx4 v130, s[56:57]
	s_mov_b32 m0, s4
	s_nop 0
	global_load_lds_dwordx4 v132, s[56:57]
	s_waitcnt vmcnt(8)
	s_waitcnt lgkmcnt(0)
	s_setprio 1
	s_barrier
	v_mfma_f32_16x16x32_bf16 v[62:65], v[140:143], v[178:181], v[62:65]
	v_mfma_f32_16x16x32_bf16 v[58:61], v[154:157], v[178:181], v[58:61]
	v_mfma_f32_16x16x32_bf16 v[46:49], v[140:143], v[186:189], v[46:49]
	v_mfma_f32_16x16x32_bf16 v[42:45], v[154:157], v[186:189], v[42:45]
	v_mfma_f32_16x16x32_bf16 v[30:33], v[140:143], v[194:197], v[30:33]
	v_mfma_f32_16x16x32_bf16 v[26:29], v[154:157], v[194:197], v[26:29]
	v_mfma_f32_16x16x32_bf16 v[14:17], v[140:143], v[202:205], v[14:17]
	v_mfma_f32_16x16x32_bf16 v[10:13], v[154:157], v[202:205], v[10:13]
	v_mfma_f32_16x16x32_bf16 v[62:65], v[144:147], v[182:185], v[62:65]
	v_mfma_f32_16x16x32_bf16 v[58:61], v[158:161], v[182:185], v[58:61]
	v_mfma_f32_16x16x32_bf16 v[46:49], v[144:147], v[190:193], v[46:49]
	v_mfma_f32_16x16x32_bf16 v[42:45], v[158:161], v[190:193], v[42:45]
	v_mfma_f32_16x16x32_bf16 v[30:33], v[144:147], v[198:201], v[30:33]
	v_mfma_f32_16x16x32_bf16 v[26:29], v[158:161], v[198:201], v[26:29]
	v_mfma_f32_16x16x32_bf16 v[14:17], v[144:147], v[206:209], v[14:17]
	v_mfma_f32_16x16x32_bf16 v[10:13], v[158:161], v[206:209], v[10:13]
	v_mfma_f32_16x16x32_bf16 v[54:57], v[162:165], v[178:181], v[54:57]
	v_mfma_f32_16x16x32_bf16 v[50:53], v[170:173], v[178:181], v[50:53]
	v_mfma_f32_16x16x32_bf16 v[38:41], v[162:165], v[186:189], v[38:41]
	v_mfma_f32_16x16x32_bf16 v[34:37], v[170:173], v[186:189], v[34:37]
	v_mfma_f32_16x16x32_bf16 v[22:25], v[162:165], v[194:197], v[22:25]
	v_mfma_f32_16x16x32_bf16 v[18:21], v[170:173], v[194:197], v[18:21]
	v_mfma_f32_16x16x32_bf16 v[6:9], v[162:165], v[202:205], v[6:9]
	v_mfma_f32_16x16x32_bf16 v[2:5], v[170:173], v[202:205], v[2:5]
	v_mfma_f32_16x16x32_bf16 v[54:57], v[166:169], v[182:185], v[54:57]
	v_mfma_f32_16x16x32_bf16 v[50:53], v[174:177], v[182:185], v[50:53]
	v_mfma_f32_16x16x32_bf16 v[38:41], v[166:169], v[190:193], v[38:41]
	v_mfma_f32_16x16x32_bf16 v[34:37], v[174:177], v[190:193], v[34:37]
	v_mfma_f32_16x16x32_bf16 v[22:25], v[166:169], v[198:201], v[22:25]
	v_mfma_f32_16x16x32_bf16 v[18:21], v[174:177], v[198:201], v[18:21]
	v_mfma_f32_16x16x32_bf16 v[6:9], v[166:169], v[206:209], v[6:9]
	v_mfma_f32_16x16x32_bf16 v[2:5], v[174:177], v[206:209], v[2:5]
	s_barrier
; #define PG8_STAGE(bufoff, gbase, voff) do { _Pragma("unroll") for (int _i = 0; _i < 2; ++_i) \
;         __builtin_amdgcn_global_load_lds((const unsigned*)((const char*)(gbase) + (voff)[_i]), (PG8_LAS unsigned*)(lds + (bufoff) + ldsw + _i * 8192), 16, 0, 0); } while (0)
; #define PG8_LDA(dst, b, h) do { _Pragma("unroll") for (int m = 0; m < 4; ++m) _Pragma("unroll") for (int k = 0; k < 2; ++k) dst[m][k] = *(const PG8_LAS bf16x8*)(lds + PG8_SA(b, h) + aoff + m * 2048 + k * 1024); } while (0)
; #define PG8_LDB(dst, b, h) do { _Pragma("unroll") for (int n = 0; n < 2; ++n) _Pragma("unroll") for (int k = 0; k < 2; ++k) dst[n][k] = *(const PG8_LAS bf16x8*)(lds + PG8_SB(b, h) + boff + n * 2048 + k * 1024); } while (0)
; #define PG8_MMA(ai, bj, At, Bt) do { __builtin_amdgcn_s_setprio(1); _Pragma("unroll") for (int m = 0; m < 4; ++m) _Pragma("unroll") for (int n = 0; n < 2; ++n) _Pragma("unroll") for (int k = 0; k < 2; ++k) \
;         acc[ai][bj][m][n] = __builtin_amdgcn_mfma_f32_16x16x32_bf16(Bt[n][k], At[m][k], acc[ai][bj][m][n], 0, 0, 0); __builtin_amdgcn_s_setprio(0); } while (0)
; #define PG8_WAIT_V(n) asm volatile("s_waitcnt vmcnt(" #n ")" ::: "memory")
; #define PG8_WAIT_L(n) asm volatile("s_waitcnt lgkmcnt(" #n ")" ::: "memory")
; #define PG8_BAR __builtin_amdgcn_s_barrier()
; #define PG8_SCHED __builtin_amdgcn_sched_barrier(0)
; template <class Epi, class Sched, bool ALIGN_EPI = false, bool SP2 = false>
; __device__ __forceinline__ void gemm_phase(PG8_LAS unsigned char* lds, const Gemm g, const Sched& S, const Epi& E) {
;     ...
;             PG8_WAIT_V(8); PG8_WAIT_L(0); PG8_BAR; PG8_MMA(1, 0, At, B0); PG8_MMA(1, 1, At, B1); PG8_BAR; PG8_SCHED;
;             PG8_LDB(B0, 1, 0); PG8_LDB(B1, 1, 1); PG8_SCHED; PG8_LDA(At, 1, 0); PG8_STAGE(PG8_SA(0, 1), a2 + hstep, voffA);
;             PG8_WAIT_V(8); PG8_WAIT_L(0); PG8_BAR; PG8_MMA(0, 0, At, B0); PG8_MMA(0, 1, At, B1); PG8_BAR; PG8_SCHED;
;             PG8_LDA(At, 1, 1); PG8_STAGE(PG8_SB(1, 0), b3, voffB); PG8_STAGE(PG8_SB(1, 1), b3 + hstep, voffB); PG8_STAGE(PG8_SA(1, 0), a3, voffA);
;             PG8_WAIT_V(8); PG8_WAIT_L(0); PG8_BAR; PG8_MMA(1, 0, At, B0); PG8_MMA(1, 1, At, B1); PG8_BAR; PG8_SCHED;
	s_setprio 0
	s_add_i32 s21, 0, 0x18000
	v_add_u32_e32 v148, s21, v151
	s_add_i32 s62, 0, 0x1c000
	ds_read_b128 v[140:143], v148
	ds_read_b128 v[144:147], v148 offset:1024
	ds_read_b128 v[154:157], v148 offset:2048
	ds_read_b128 v[158:161], v148 offset:3072
	v_add_u32_e32 v148, s62, v151
	ds_read_b128 v[162:165], v148
	ds_read_b128 v[166:169], v148 offset:1024
	ds_read_b128 v[170:173], v148 offset:2048
	ds_read_b128 v[174:177], v148 offset:3072
	s_add_u32 s56, s56, 0x80000
	s_addc_u32 s57, s57, 0
	s_mov_b32 m0, s5
	ds_read_b128 v[178:181], v153 offset:32768
	ds_read_b128 v[182:185], v153 offset:33792
	ds_read_b128 v[186:189], v153 offset:34816
	ds_read_b128 v[190:193], v153 offset:35840
	ds_read_b128 v[194:197], v153 offset:36864
	ds_read_b128 v[198:201], v153 offset:37888
	ds_read_b128 v[202:205], v153 offset:38912
	ds_read_b128 v[206:209], v153 offset:39936
	global_load_lds_dwordx4 v130, s[56:57]
	s_mov_b32 m0, s6
	s_nop 0
	global_load_lds_dwordx4 v132, s[56:57]
	s_waitcnt vmcnt(8)
	s_waitcnt lgkmcnt(0)
	s_setprio 1
	s_barrier
	v_mfma_f32_16x16x32_bf16 v[126:129], v[140:143], v[178:181], v[126:129]
	v_mfma_f32_16x16x32_bf16 v[122:125], v[154:157], v[178:181], v[122:125]
	v_mfma_f32_16x16x32_bf16 v[110:113], v[140:143], v[186:189], v[110:113]
	v_mfma_f32_16x16x32_bf16 v[106:109], v[154:157], v[186:189], v[106:109]
	v_mfma_f32_16x16x32_bf16 v[94:97], v[140:143], v[194:197], v[94:97]
	v_mfma_f32_16x16x32_bf16 v[90:93], v[154:157], v[194:197], v[90:93]
	v_mfma_f32_16x16x32_bf16 v[78:81], v[140:143], v[202:205], v[78:81]
	v_mfma_f32_16x16x32_bf16 v[74:77], v[154:157], v[202:205], v[74:77]
	v_mfma_f32_16x16x32_bf16 v[126:129], v[144:147], v[182:185], v[126:129]
	v_mfma_f32_16x16x32_bf16 v[122:125], v[158:161], v[182:185], v[122:125]
	v_mfma_f32_16x16x32_bf16 v[110:113], v[144:147], v[190:193], v[110:113]
	v_mfma_f32_16x16x32_bf16 v[106:109], v[158:161], v[190:193], v[106:109]
	v_mfma_f32_16x16x32_bf16 v[94:97], v[144:147], v[198:201], v[94:97]
	v_mfma_f32_16x16x32_bf16 v[90:93], v[158:161], v[198:201], v[90:93]
	v_mfma_f32_16x16x32_bf16 v[78:81], v[144:147], v[206:209], v[78:81]
	v_mfma_f32_16x16x32_bf16 v[74:77], v[158:161], v[206:209], v[74:77]
	v_mfma_f32_16x16x32_bf16 v[118:121], v[162:165], v[178:181], v[118:121]
	v_mfma_f32_16x16x32_bf16 v[114:117], v[170:173], v[178:181], v[114:117]
	v_mfma_f32_16x16x32_bf16 v[102:105], v[162:165], v[186:189], v[102:105]
	v_mfma_f32_16x16x32_bf16 v[98:101], v[170:173], v[186:189], v[98:101]
	v_mfma_f32_16x16x32_bf16 v[86:89], v[162:165], v[194:197], v[86:89]
	v_mfma_f32_16x16x32_bf16 v[82:85], v[170:173], v[194:197], v[82:85]
	v_mfma_f32_16x16x32_bf16 v[70:73], v[162:165], v[202:205], v[70:73]
	v_mfma_f32_16x16x32_bf16 v[66:69], v[170:173], v[202:205], v[66:69]
	v_mfma_f32_16x16x32_bf16 v[118:121], v[166:169], v[182:185], v[118:121]
	v_mfma_f32_16x16x32_bf16 v[114:117], v[174:177], v[182:185], v[114:117]
	v_mfma_f32_16x16x32_bf16 v[102:105], v[166:169], v[190:193], v[102:105]
	v_mfma_f32_16x16x32_bf16 v[98:101], v[174:177], v[190:193], v[98:101]
	v_mfma_f32_16x16x32_bf16 v[86:89], v[166:169], v[198:201], v[86:89]
	v_mfma_f32_16x16x32_bf16 v[82:85], v[174:177], v[198:201], v[82:85]
	v_mfma_f32_16x16x32_bf16 v[70:73], v[166:169], v[206:209], v[70:73]
	v_mfma_f32_16x16x32_bf16 v[66:69], v[174:177], v[206:209], v[66:69]
	s_barrier
	s_setprio 0
	s_add_i32 s21, s21, s1
	s_mov_b32 m0, s21
	ds_read_b128 v[178:181], v153 offset:49152
	ds_read_b128 v[182:185], v153 offset:50176
	ds_read_b128 v[186:189], v153 offset:51200
	ds_read_b128 v[190:193], v153 offset:52224
	ds_read_b128 v[194:197], v153 offset:53248
	ds_read_b128 v[198:201], v153 offset:54272
	ds_read_b128 v[202:205], v153 offset:55296
	ds_read_b128 v[206:209], v153 offset:56320
	global_load_lds_dwordx4 v0, s[100:101]
	s_add_i32 m0, s21, 0x2000
	s_add_i32 s21, s62, s1
	global_load_lds_dwordx4 v134, s[100:101]
	s_add_u32 s10, s10, 0x80080
	s_addc_u32 s11, s11, 0
	s_mov_b32 m0, s21
	s_nop 0
	global_load_lds_dwordx4 v0, s[10:11]
	s_add_i32 m0, s21, 0x2000
	s_nop 0
	global_load_lds_dwordx4 v134, s[10:11]
	s_mov_b32 m0, s7
	s_nop 0
	global_load_lds_dwordx4 v130, s[98:99]
	s_mov_b32 m0, s30
	s_nop 0
	global_load_lds_dwordx4 v132, s[98:99]
	s_waitcnt vmcnt(8)
	s_waitcnt lgkmcnt(0)
	s_setprio 1
	s_barrier
	v_mfma_f32_16x16x32_bf16 v[62:65], v[140:143], v[178:181], v[62:65]
	v_mfma_f32_16x16x32_bf16 v[58:61], v[154:157], v[178:181], v[58:61]
	v_mfma_f32_16x16x32_bf16 v[46:49], v[140:143], v[186:189], v[46:49]
	v_mfma_f32_16x16x32_bf16 v[42:45], v[154:157], v[186:189], v[42:45]
	v_mfma_f32_16x16x32_bf16 v[30:33], v[140:143], v[194:197], v[30:33]
	v_mfma_f32_16x16x32_bf16 v[26:29], v[154:157], v[194:197], v[26:29]
	v_mfma_f32_16x16x32_bf16 v[14:17], v[140:143], v[202:205], v[14:17]
	v_mfma_f32_16x16x32_bf16 v[10:13], v[154:157], v[202:205], v[10:13]
	v_mfma_f32_16x16x32_bf16 v[62:65], v[144:147], v[182:185], v[62:65]
	v_mfma_f32_16x16x32_bf16 v[58:61], v[158:161], v[182:185], v[58:61]
	v_mfma_f32_16x16x32_bf16 v[46:49], v[144:147], v[190:193], v[46:49]
	v_mfma_f32_16x16x32_bf16 v[42:45], v[158:161], v[190:193], v[42:45]
	v_mfma_f32_16x16x32_bf16 v[30:33], v[144:147], v[198:201], v[30:33]
	v_mfma_f32_16x16x32_bf16 v[26:29], v[158:161], v[198:201], v[26:29]
	v_mfma_f32_16x16x32_bf16 v[14:17], v[144:147], v[206:209], v[14:17]
	v_mfma_f32_16x16x32_bf16 v[10:13], v[158:161], v[206:209], v[10:13]
	v_mfma_f32_16x16x32_bf16 v[54:57], v[162:165], v[178:181], v[54:57]
	v_mfma_f32_16x16x32_bf16 v[50:53], v[170:173], v[178:181], v[50:53]
	v_mfma_f32_16x16x32_bf16 v[38:41], v[162:165], v[186:189], v[38:41]
	v_mfma_f32_16x16x32_bf16 v[34:37], v[170:173], v[186:189], v[34:37]
	v_mfma_f32_16x16x32_bf16 v[22:25], v[162:165], v[194:197], v[22:25]
	v_mfma_f32_16x16x32_bf16 v[18:21], v[170:173], v[194:197], v[18:21]
	v_mfma_f32_16x16x32_bf16 v[6:9], v[162:165], v[202:205], v[6:9]
	v_mfma_f32_16x16x32_bf16 v[2:5], v[170:173], v[202:205], v[2:5]
	v_mfma_f32_16x16x32_bf16 v[54:57], v[166:169], v[182:185], v[54:57]
	v_mfma_f32_16x16x32_bf16 v[50:53], v[174:177], v[182:185], v[50:53]
	v_mfma_f32_16x16x32_bf16 v[38:41], v[166:169], v[190:193], v[38:41]
	v_mfma_f32_16x16x32_bf16 v[34:37], v[174:177], v[190:193], v[34:37]
	v_mfma_f32_16x16x32_bf16 v[22:25], v[166:169], v[198:201], v[22:25]
	v_mfma_f32_16x16x32_bf16 v[18:21], v[174:177], v[198:201], v[18:21]
	v_mfma_f32_16x16x32_bf16 v[6:9], v[166:169], v[206:209], v[6:9]
	v_mfma_f32_16x16x32_bf16 v[2:5], v[174:177], v[206:209], v[2:5]
	s_barrier
	s_setprio 0
	s_add_i32 s13, s13, 2
	s_add_u32 s16, s16, 0x100
	s_addc_u32 s17, s17, 0
	s_add_u32 s61, s61, 0x100
	s_addc_u32 s12, s12, 0
	s_cmp_gt_u32 s13, 29
	s_cbranch_scc0 .LBB0_169
	s_and_b64 vcc, exec, s[22:23]
	s_cbranch_vccz .LBB0_172
	s_barrier

; #define PG8_STAGE(bufoff, gbase, voff) do { _Pragma("unroll") for (int _i = 0; _i < 2; ++_i) \
;         __builtin_amdgcn_global_load_lds((const unsigned*)((const char*)(gbase) + (voff)[_i]), (PG8_LAS unsigned*)(lds + (bufoff) + ldsw + _i * 8192), 16, 0, 0); } while (0)
; #define PG8_LDA(dst, b, h) do { _Pragma("unroll") for (int m = 0; m < 4; ++m) _Pragma("unroll") for (int k = 0; k < 2; ++k) dst[m][k] = *(const PG8_LAS bf16x8*)(lds + PG8_SA(b, h) + aoff + m * 2048 + k * 1024); } while (0)
; #define PG8_LDB(dst, b, h) do { _Pragma("unroll") for (int n = 0; n < 2; ++n) _Pragma("unroll") for (int k = 0; k < 2; ++k) dst[n][k] = *(const PG8_LAS bf16x8*)(lds + PG8_SB(b, h) + boff + n * 2048 + k * 1024); } while (0)
; #define PG8_WAIT_V(n) asm volatile("s_waitcnt vmcnt(" #n ")" ::: "memory")
; #define PG8_WAIT_L(n) asm volatile("s_waitcnt lgkmcnt(" #n ")" ::: "memory")
; #define PG8_BAR __builtin_amdgcn_s_barrier()
; #define PG8_SCHED __builtin_amdgcn_sched_barrier(0)
; template <class Epi, class Sched, bool ALIGN_EPI = false, bool SP2 = false>
; __device__ __forceinline__ void gemm_phase(PG8_LAS unsigned char* lds, const Gemm g, const Sched& S, const Epi& E) {
;     ...
;         const bool has_next = S.next(ui + 1, nxt);
;         const char* nA = has_next ? (const char*)g.A + (size_t)nxt.pm * tstep : cA; const char* nB = has_next ? (const char*)g.Bt + (size_t)nxt.pn * tstep : cB;
;         for (int t = 0; t < nt; t += 2) {
;             const bool last = (t == nt - 2);
;             const char* a1 = cA + (size_t)(t + 1) * kstep;
;             const char* a2 = last ? nA : cA + (size_t)(t + 2) * kstep; const char* b2 = last ? nB : cB + (size_t)(t + 2) * kstep;
;             const char* a3 = a2 + kstep; const char* b3 = b2 + kstep;
;             if (last && has_next) S.a_ready(nxt);
;             if constexpr (SP2) {
;             PG8_LDB(B0, 0, 0); PG8_LDB(B1, 0, 1); PG8_SCHED; PG8_LDA(At, 0, 0); PG8_STAGE(PG8_SA(1, 1), a1 + hstep, voffA);
;             PG8_WAIT_V(8); PG8_WAIT_L(0); PG8_BAR; PG8_MMA(0, 0, At, B0); PG8_MMA(0, 1, At, B1); PG8_BAR; PG8_SCHED;
;             PG8_LDA(At, 0, 1); PG8_STAGE(PG8_SB(0, 0), b2, voffB); PG8_STAGE(PG8_SB(0, 1), b2 + hstep, voffB); PG8_STAGE(PG8_SA(0, 0), a2, voffA);
;             PG8_WAIT_V(8); PG8_WAIT_L(0); PG8_BAR; PG8_MMA(1, 0, At, B0); PG8_MMA(1, 1, At, B1); PG8_BAR; PG8_SCHED;
.LBB0_559:
	s_add_u32 s10, s50, 0xfff80080
	s_addc_u32 s11, s51, -1
	s_add_i32 s60, 0, 0x10000
	s_cmp_eq_u32 s59, 28
	s_cselect_b32 s53, s37, s11
	s_cselect_b32 s52, s43, s10
	v_add_u32_e32 v144, s60, v149
	s_cselect_b32 s11, s23, s58
	s_cselect_b32 s10, s56, s57
	s_add_i32 s62, 0, 0x14000
	ds_read_b128 v[140:143], v144
	ds_read_b128 v[152:155], v144 offset:1024
	ds_read_b128 v[156:159], v144 offset:2048
	ds_read_b128 v[160:163], v144 offset:3072
	v_add_u32_e32 v144, s62, v149
	ds_read_b128 v[164:167], v144
	ds_read_b128 v[168:171], v144 offset:1024
	ds_read_b128 v[172:175], v144 offset:2048
	ds_read_b128 v[176:179], v144 offset:3072
	s_add_i32 m0, s5, 0xc000
	ds_read_b128 v[180:183], v151
	ds_read_b128 v[184:187], v151 offset:1024
	ds_read_b128 v[188:191], v151 offset:2048
	ds_read_b128 v[192:195], v151 offset:3072
	ds_read_b128 v[196:199], v151 offset:4096
	ds_read_b128 v[200:203], v151 offset:5120
	ds_read_b128 v[204:207], v151 offset:6144
	ds_read_b128 v[208:211], v151 offset:7168
	global_load_lds_dwordx4 v136, s[50:51]
	s_add_i32 m0, s5, 0xe000
	s_nop 0
	global_load_lds_dwordx4 v138, s[50:51]
	s_waitcnt vmcnt(8)
	s_waitcnt lgkmcnt(0)
	s_setprio 1
	s_barrier
	v_mfma_f32_16x16x32_bf16 v[126:129], v[140:143], v[180:183], v[126:129]
	v_mfma_f32_16x16x32_bf16 v[122:125], v[156:159], v[180:183], v[122:125]
	v_mfma_f32_16x16x32_bf16 v[110:113], v[140:143], v[188:191], v[110:113]
	v_mfma_f32_16x16x32_bf16 v[106:109], v[156:159], v[188:191], v[106:109]
	v_mfma_f32_16x16x32_bf16 v[94:97], v[140:143], v[196:199], v[94:97]
	v_mfma_f32_16x16x32_bf16 v[90:93], v[156:159], v[196:199], v[90:93]
	v_mfma_f32_16x16x32_bf16 v[78:81], v[140:143], v[204:207], v[78:81]
	v_mfma_f32_16x16x32_bf16 v[74:77], v[156:159], v[204:207], v[74:77]
	v_mfma_f32_16x16x32_bf16 v[126:129], v[152:155], v[184:187], v[126:129]
	v_mfma_f32_16x16x32_bf16 v[122:125], v[160:163], v[184:187], v[122:125]
	v_mfma_f32_16x16x32_bf16 v[110:113], v[152:155], v[192:195], v[110:113]
	v_mfma_f32_16x16x32_bf16 v[106:109], v[160:163], v[192:195], v[106:109]
	v_mfma_f32_16x16x32_bf16 v[94:97], v[152:155], v[200:203], v[94:97]
	v_mfma_f32_16x16x32_bf16 v[90:93], v[160:163], v[200:203], v[90:93]
	v_mfma_f32_16x16x32_bf16 v[78:81], v[152:155], v[208:211], v[78:81]
	v_mfma_f32_16x16x32_bf16 v[74:77], v[160:163], v[208:211], v[74:77]
	v_mfma_f32_16x16x32_bf16 v[118:121], v[164:167], v[180:183], v[118:121]
	v_mfma_f32_16x16x32_bf16 v[114:117], v[172:175], v[180:183], v[114:117]
	v_mfma_f32_16x16x32_bf16 v[102:105], v[164:167], v[188:191], v[102:105]
	v_mfma_f32_16x16x32_bf16 v[98:101], v[172:175], v[188:191], v[98:101]
	v_mfma_f32_16x16x32_bf16 v[86:89], v[164:167], v[196:199], v[86:89]
	v_mfma_f32_16x16x32_bf16 v[82:85], v[172:175], v[196:199], v[82:85]
	v_mfma_f32_16x16x32_bf16 v[70:73], v[164:167], v[204:207], v[70:73]
	v_mfma_f32_16x16x32_bf16 v[66:69], v[172:175], v[204:207], v[66:69]
	v_mfma_f32_16x16x32_bf16 v[118:121], v[168:171], v[184:187], v[118:121]
	v_mfma_f32_16x16x32_bf16 v[114:117], v[176:179], v[184:187], v[114:117]
	v_mfma_f32_16x16x32_bf16 v[102:105], v[168:171], v[192:195], v[102:105]
	v_mfma_f32_16x16x32_bf16 v[98:101], v[176:179], v[192:195], v[98:101]
	v_mfma_f32_16x16x32_bf16 v[86:89], v[168:171], v[200:203], v[86:89]
	v_mfma_f32_16x16x32_bf16 v[82:85], v[176:179], v[200:203], v[82:85]
	v_mfma_f32_16x16x32_bf16 v[70:73], v[168:171], v[208:211], v[70:73]
	v_mfma_f32_16x16x32_bf16 v[66:69], v[176:179], v[208:211], v[66:69]
	s_barrier
	s_setprio 0
	s_add_i32 s60, s60, s4
	s_add_u32 s100, s10, 0x80
	s_addc_u32 s101, s11, 0
	s_mov_b32 m0, s60
	ds_read_b128 v[180:183], v151 offset:16384
	ds_read_b128 v[184:187], v151 offset:17408
	ds_read_b128 v[188:191], v151 offset:18432
	ds_read_b128 v[192:195], v151 offset:19456
	ds_read_b128 v[196:199], v151 offset:20480
	ds_read_b128 v[200:203], v151 offset:21504
	ds_read_b128 v[204:207], v151 offset:22528
	ds_read_b128 v[208:211], v151 offset:23552
	global_load_lds_dwordx4 v0, s[10:11]
	s_add_i32 m0, s60, 0x2000
	s_add_u32 s60, s10, 0x80000
	s_addc_u32 s61, s11, 0
	s_add_i32 s62, s62, s4
	global_load_lds_dwordx4 v134, s[10:11]
	s_mov_b32 m0, s62
	s_add_u32 s98, s52, 0x80
	s_addc_u32 s99, s53, 0
	global_load_lds_dwordx4 v0, s[60:61]
	s_add_i32 m0, s62, 0x2000
	s_nop 0
	global_load_lds_dwordx4 v134, s[60:61]
	s_mov_b32 m0, s5
	s_nop 0
	global_load_lds_dwordx4 v130, s[52:53]
	s_mov_b32 m0, s6
	s_nop 0
	global_load_lds_dwordx4 v132, s[52:53]
	s_waitcnt vmcnt(8)
	s_waitcnt lgkmcnt(0)
	s_setprio 1
	s_barrier
	v_mfma_f32_16x16x32_bf16 v[62:65], v[140:143], v[180:183], v[62:65]
	v_mfma_f32_16x16x32_bf16 v[58:61], v[156:159], v[180:183], v[58:61]
	v_mfma_f32_16x16x32_bf16 v[46:49], v[140:143], v[188:191], v[46:49]
	v_mfma_f32_16x16x32_bf16 v[42:45], v[156:159], v[188:191], v[42:45]
	v_mfma_f32_16x16x32_bf16 v[30:33], v[140:143], v[196:199], v[30:33]
	v_mfma_f32_16x16x32_bf16 v[26:29], v[156:159], v[196:199], v[26:29]
	v_mfma_f32_16x16x32_bf16 v[14:17], v[140:143], v[204:207], v[14:17]
	v_mfma_f32_16x16x32_bf16 v[10:13], v[156:159], v[204:207], v[10:13]
	v_mfma_f32_16x16x32_bf16 v[62:65], v[152:155], v[184:187], v[62:65]
	v_mfma_f32_16x16x32_bf16 v[58:61], v[160:163], v[184:187], v[58:61]
	v_mfma_f32_16x16x32_bf16 v[46:49], v[152:155], v[192:195], v[46:49]
	v_mfma_f32_16x16x32_bf16 v[42:45], v[160:163], v[192:195], v[42:45]
	v_mfma_f32_16x16x32_bf16 v[30:33], v[152:155], v[200:203], v[30:33]
	v_mfma_f32_16x16x32_bf16 v[26:29], v[160:163], v[200:203], v[26:29]
	v_mfma_f32_16x16x32_bf16 v[14:17], v[152:155], v[208:211], v[14:17]
	v_mfma_f32_16x16x32_bf16 v[10:13], v[160:163], v[208:211], v[10:13]
	v_mfma_f32_16x16x32_bf16 v[54:57], v[164:167], v[180:183], v[54:57]
	v_mfma_f32_16x16x32_bf16 v[50:53], v[172:175], v[180:183], v[50:53]
	v_mfma_f32_16x16x32_bf16 v[38:41], v[164:167], v[188:191], v[38:41]
	v_mfma_f32_16x16x32_bf16 v[34:37], v[172:175], v[188:191], v[34:37]
	v_mfma_f32_16x16x32_bf16 v[22:25], v[164:167], v[196:199], v[22:25]
	v_mfma_f32_16x16x32_bf16 v[18:21], v[172:175], v[196:199], v[18:21]
	v_mfma_f32_16x16x32_bf16 v[6:9], v[164:167], v[204:207], v[6:9]
	v_mfma_f32_16x16x32_bf16 v[2:5], v[172:175], v[204:207], v[2:5]
	v_mfma_f32_16x16x32_bf16 v[54:57], v[168:171], v[184:187], v[54:57]
	v_mfma_f32_16x16x32_bf16 v[50:53], v[176:179], v[184:187], v[50:53]
	v_mfma_f32_16x16x32_bf16 v[38:41], v[168:171], v[192:195], v[38:41]
	v_mfma_f32_16x16x32_bf16 v[34:37], v[176:179], v[192:195], v[34:37]
	v_mfma_f32_16x16x32_bf16 v[22:25], v[168:171], v[200:203], v[22:25]
	v_mfma_f32_16x16x32_bf16 v[18:21], v[176:179], v[200:203], v[18:21]
	v_mfma_f32_16x16x32_bf16 v[6:9], v[168:171], v[208:211], v[6:9]
	v_mfma_f32_16x16x32_bf16 v[2:5], v[176:179], v[208:211], v[2:5]
	s_barrier
; #define PG8_STAGE(bufoff, gbase, voff) do { _Pragma("unroll") for (int _i = 0; _i < 2; ++_i) \
;         __builtin_amdgcn_global_load_lds((const unsigned*)((const char*)(gbase) + (voff)[_i]), (PG8_LAS unsigned*)(lds + (bufoff) + ldsw + _i * 8192), 16, 0, 0); } while (0)
; #define PG8_LDA(dst, b, h) do { _Pragma("unroll") for (int m = 0; m < 4; ++m) _Pragma("unroll") for (int k = 0; k < 2; ++k) dst[m][k] = *(const PG8_LAS bf16x8*)(lds + PG8_SA(b, h) + aoff + m * 2048 + k * 1024); } while (0)
; #define PG8_LDB(dst, b, h) do { _Pragma("unroll") for (int n = 0; n < 2; ++n) _Pragma("unroll") for (int k = 0; k < 2; ++k) dst[n][k] = *(const PG8_LAS bf16x8*)(lds + PG8_SB(b, h) + boff + n * 2048 + k * 1024); } while (0)
; #define PG8_MMA(ai, bj, At, Bt) do { __builtin_amdgcn_s_setprio(1); _Pragma("unroll") for (int m = 0; m < 4; ++m) _Pragma("unroll") for (int n = 0; n < 2; ++n) _Pragma("unroll") for (int k = 0; k < 2; ++k) \
;         acc[ai][bj][m][n] = __builtin_amdgcn_mfma_f32_16x16x32_bf16(Bt[n][k], At[m][k], acc[ai][bj][m][n], 0, 0, 0); __builtin_amdgcn_s_setprio(0); } while (0)
; #define PG8_WAIT_V(n) asm volatile("s_waitcnt vmcnt(" #n ")" ::: "memory")
; #define PG8_WAIT_L(n) asm volatile("s_waitcnt lgkmcnt(" #n ")" ::: "memory")
; #define PG8_BAR __builtin_amdgcn_s_barrier()
; #define PG8_SCHED __builtin_amdgcn_sched_barrier(0)
; template <class Epi, class Sched, bool ALIGN_EPI = false, bool SP2 = false>
; __device__ __forceinline__ void gemm_phase(PG8_LAS unsigned char* lds, const Gemm g, const Sched& S, const Epi& E) {
;     ...
;             PG8_WAIT_V(8); PG8_WAIT_L(0); PG8_BAR; PG8_MMA(1, 0, At, B0); PG8_MMA(1, 1, At, B1); PG8_BAR; PG8_SCHED;
;             PG8_LDB(B0, 1, 0); PG8_LDB(B1, 1, 1); PG8_SCHED; PG8_LDA(At, 1, 0); PG8_STAGE(PG8_SA(0, 1), a2 + hstep, voffA);
;             PG8_WAIT_V(8); PG8_WAIT_L(0); PG8_BAR; PG8_MMA(0, 0, At, B0); PG8_MMA(0, 1, At, B1); PG8_BAR; PG8_SCHED;
;             PG8_LDA(At, 1, 1); PG8_STAGE(PG8_SB(1, 0), b3, voffB); PG8_STAGE(PG8_SB(1, 1), b3 + hstep, voffB); PG8_STAGE(PG8_SA(1, 0), a3, voffA);
;             PG8_WAIT_V(8); PG8_WAIT_L(0); PG8_BAR; PG8_MMA(1, 0, At, B0); PG8_MMA(1, 1, At, B1); PG8_BAR; PG8_SCHED;
	s_setprio 0
	s_add_i32 s60, 0, 0x18000
	v_add_u32_e32 v146, s60, v149
	s_add_i32 s61, 0, 0x1c000
	ds_read_b128 v[140:143], v146
	ds_read_b128 v[152:155], v146 offset:1024
	ds_read_b128 v[156:159], v146 offset:2048
	ds_read_b128 v[160:163], v146 offset:3072
	v_add_u32_e32 v146, s61, v149
	ds_read_b128 v[164:167], v146
	ds_read_b128 v[168:171], v146 offset:1024
	ds_read_b128 v[172:175], v146 offset:2048
	ds_read_b128 v[176:179], v146 offset:3072
	s_add_u32 s52, s52, 0x80000
	s_addc_u32 s53, s53, 0
	s_mov_b32 m0, s7
	ds_read_b128 v[180:183], v151 offset:32768
	ds_read_b128 v[184:187], v151 offset:33792
	ds_read_b128 v[188:191], v151 offset:34816
	ds_read_b128 v[192:195], v151 offset:35840
	ds_read_b128 v[196:199], v151 offset:36864
	ds_read_b128 v[200:203], v151 offset:37888
	ds_read_b128 v[204:207], v151 offset:38912
	ds_read_b128 v[208:211], v151 offset:39936
	global_load_lds_dwordx4 v130, s[52:53]
	s_mov_b32 m0, s17
	s_nop 0
	global_load_lds_dwordx4 v132, s[52:53]
	s_waitcnt vmcnt(8)
	s_waitcnt lgkmcnt(0)
	s_setprio 1
	s_barrier
	v_mfma_f32_16x16x32_bf16 v[126:129], v[140:143], v[180:183], v[126:129]
	v_mfma_f32_16x16x32_bf16 v[122:125], v[156:159], v[180:183], v[122:125]
	v_mfma_f32_16x16x32_bf16 v[110:113], v[140:143], v[188:191], v[110:113]
	v_mfma_f32_16x16x32_bf16 v[106:109], v[156:159], v[188:191], v[106:109]
	v_mfma_f32_16x16x32_bf16 v[94:97], v[140:143], v[196:199], v[94:97]
	v_mfma_f32_16x16x32_bf16 v[90:93], v[156:159], v[196:199], v[90:93]
	v_mfma_f32_16x16x32_bf16 v[78:81], v[140:143], v[204:207], v[78:81]
	v_mfma_f32_16x16x32_bf16 v[74:77], v[156:159], v[204:207], v[74:77]
	v_mfma_f32_16x16x32_bf16 v[126:129], v[152:155], v[184:187], v[126:129]
	v_mfma_f32_16x16x32_bf16 v[122:125], v[160:163], v[184:187], v[122:125]
	v_mfma_f32_16x16x32_bf16 v[110:113], v[152:155], v[192:195], v[110:113]
	v_mfma_f32_16x16x32_bf16 v[106:109], v[160:163], v[192:195], v[106:109]
	v_mfma_f32_16x16x32_bf16 v[94:97], v[152:155], v[200:203], v[94:97]
	v_mfma_f32_16x16x32_bf16 v[90:93], v[160:163], v[200:203], v[90:93]
	v_mfma_f32_16x16x32_bf16 v[78:81], v[152:155], v[208:211], v[78:81]
	v_mfma_f32_16x16x32_bf16 v[74:77], v[160:163], v[208:211], v[74:77]
	v_mfma_f32_16x16x32_bf16 v[118:121], v[164:167], v[180:183], v[118:121]
	v_mfma_f32_16x16x32_bf16 v[114:117], v[172:175], v[180:183], v[114:117]
	v_mfma_f32_16x16x32_bf16 v[102:105], v[164:167], v[188:191], v[102:105]
	v_mfma_f32_16x16x32_bf16 v[98:101], v[172:175], v[188:191], v[98:101]
	v_mfma_f32_16x16x32_bf16 v[86:89], v[164:167], v[196:199], v[86:89]
	v_mfma_f32_16x16x32_bf16 v[82:85], v[172:175], v[196:199], v[82:85]
	v_mfma_f32_16x16x32_bf16 v[70:73], v[164:167], v[204:207], v[70:73]
	v_mfma_f32_16x16x32_bf16 v[66:69], v[172:175], v[204:207], v[66:69]
	v_mfma_f32_16x16x32_bf16 v[118:121], v[168:171], v[184:187], v[118:121]
	v_mfma_f32_16x16x32_bf16 v[114:117], v[176:179], v[184:187], v[114:117]
	v_mfma_f32_16x16x32_bf16 v[102:105], v[168:171], v[192:195], v[102:105]
	v_mfma_f32_16x16x32_bf16 v[98:101], v[176:179], v[192:195], v[98:101]
	v_mfma_f32_16x16x32_bf16 v[86:89], v[168:171], v[200:203], v[86:89]
	v_mfma_f32_16x16x32_bf16 v[82:85], v[176:179], v[200:203], v[82:85]
	v_mfma_f32_16x16x32_bf16 v[70:73], v[168:171], v[208:211], v[70:73]
	v_mfma_f32_16x16x32_bf16 v[66:69], v[176:179], v[208:211], v[66:69]
	s_barrier
	s_setprio 0
	s_add_i32 s52, s60, s4
	s_mov_b32 m0, s52
	ds_read_b128 v[180:183], v151 offset:49152
	ds_read_b128 v[184:187], v151 offset:50176
	ds_read_b128 v[188:191], v151 offset:51200
	ds_read_b128 v[192:195], v151 offset:52224
	ds_read_b128 v[196:199], v151 offset:53248
	ds_read_b128 v[200:203], v151 offset:54272
	ds_read_b128 v[204:207], v151 offset:55296
	ds_read_b128 v[208:211], v151 offset:56320
	global_load_lds_dwordx4 v0, s[100:101]
	s_add_i32 m0, s52, 0x2000
	s_add_i32 s52, s61, s4
	global_load_lds_dwordx4 v134, s[100:101]
	s_add_u32 s10, s10, 0x80080
	s_addc_u32 s11, s11, 0
	s_mov_b32 m0, s52
	s_nop 0
	global_load_lds_dwordx4 v0, s[10:11]
	s_add_i32 m0, s52, 0x2000
	s_nop 0
	global_load_lds_dwordx4 v134, s[10:11]
	s_mov_b32 m0, s30
	s_nop 0
	global_load_lds_dwordx4 v130, s[98:99]
	s_mov_b32 m0, s47
	s_nop 0
	global_load_lds_dwordx4 v132, s[98:99]
	s_waitcnt vmcnt(8)
	s_waitcnt lgkmcnt(0)
	s_setprio 1
	s_barrier
	v_mfma_f32_16x16x32_bf16 v[62:65], v[140:143], v[180:183], v[62:65]
	v_mfma_f32_16x16x32_bf16 v[58:61], v[156:159], v[180:183], v[58:61]
	v_mfma_f32_16x16x32_bf16 v[46:49], v[140:143], v[188:191], v[46:49]
	v_mfma_f32_16x16x32_bf16 v[42:45], v[156:159], v[188:191], v[42:45]
	v_mfma_f32_16x16x32_bf16 v[30:33], v[140:143], v[196:199], v[30:33]
	v_mfma_f32_16x16x32_bf16 v[26:29], v[156:159], v[196:199], v[26:29]
	v_mfma_f32_16x16x32_bf16 v[14:17], v[140:143], v[204:207], v[14:17]
	v_mfma_f32_16x16x32_bf16 v[10:13], v[156:159], v[204:207], v[10:13]
	v_mfma_f32_16x16x32_bf16 v[62:65], v[152:155], v[184:187], v[62:65]
	v_mfma_f32_16x16x32_bf16 v[58:61], v[160:163], v[184:187], v[58:61]
	v_mfma_f32_16x16x32_bf16 v[46:49], v[152:155], v[192:195], v[46:49]
	v_mfma_f32_16x16x32_bf16 v[42:45], v[160:163], v[192:195], v[42:45]
	v_mfma_f32_16x16x32_bf16 v[30:33], v[152:155], v[200:203], v[30:33]
	v_mfma_f32_16x16x32_bf16 v[26:29], v[160:163], v[200:203], v[26:29]
	v_mfma_f32_16x16x32_bf16 v[14:17], v[152:155], v[208:211], v[14:17]
	v_mfma_f32_16x16x32_bf16 v[10:13], v[160:163], v[208:211], v[10:13]
	v_mfma_f32_16x16x32_bf16 v[54:57], v[164:167], v[180:183], v[54:57]
	v_mfma_f32_16x16x32_bf16 v[50:53], v[172:175], v[180:183], v[50:53]
	v_mfma_f32_16x16x32_bf16 v[38:41], v[164:167], v[188:191], v[38:41]
	v_mfma_f32_16x16x32_bf16 v[34:37], v[172:175], v[188:191], v[34:37]
	v_mfma_f32_16x16x32_bf16 v[22:25], v[164:167], v[196:199], v[22:25]
	v_mfma_f32_16x16x32_bf16 v[18:21], v[172:175], v[196:199], v[18:21]
	v_mfma_f32_16x16x32_bf16 v[6:9], v[164:167], v[204:207], v[6:9]
	v_mfma_f32_16x16x32_bf16 v[2:5], v[172:175], v[204:207], v[2:5]
	v_mfma_f32_16x16x32_bf16 v[54:57], v[168:171], v[184:187], v[54:57]
	v_mfma_f32_16x16x32_bf16 v[50:53], v[176:179], v[184:187], v[50:53]
	v_mfma_f32_16x16x32_bf16 v[38:41], v[168:171], v[192:195], v[38:41]
	v_mfma_f32_16x16x32_bf16 v[34:37], v[176:179], v[192:195], v[34:37]
	v_mfma_f32_16x16x32_bf16 v[22:25], v[168:171], v[200:203], v[22:25]
	v_mfma_f32_16x16x32_bf16 v[18:21], v[176:179], v[200:203], v[18:21]
	v_mfma_f32_16x16x32_bf16 v[6:9], v[168:171], v[208:211], v[6:9]
	v_mfma_f32_16x16x32_bf16 v[2:5], v[176:179], v[208:211], v[2:5]
	s_barrier
	s_setprio 0
	s_add_i32 s59, s59, 2
	s_add_u32 s50, s50, 0x100
	s_addc_u32 s51, s51, 0
	s_add_u32 s57, s57, 0x100
	s_addc_u32 s58, s58, 0
	s_cmp_gt_u32 s59, 29
	s_cbranch_scc0 .LBB0_559
	s_and_b64 vcc, exec, s[14:15]
	s_cbranch_vccz .LBB0_562
	s_barrier

; #define PG8_STAGE(bufoff, gbase, voff) do { _Pragma("unroll") for (int _i = 0; _i < 2; ++_i) \
;         __builtin_amdgcn_global_load_lds((const unsigned*)((const char*)(gbase) + (voff)[_i]), (PG8_LAS unsigned*)(lds + (bufoff) + ldsw + _i * 8192), 16, 0, 0); } while (0)
; #define PG8_LDA(dst, b, h) do { _Pragma("unroll") for (int m = 0; m < 4; ++m) _Pragma("unroll") for (int k = 0; k < 2; ++k) dst[m][k] = *(const PG8_LAS bf16x8*)(lds + PG8_SA(b, h) + aoff + m * 2048 + k * 1024); } while (0)
; #define PG8_LDB(dst, b, h) do { _Pragma("unroll") for (int n = 0; n < 2; ++n) _Pragma("unroll") for (int k = 0; k < 2; ++k) dst[n][k] = *(const PG8_LAS bf16x8*)(lds + PG8_SB(b, h) + boff + n * 2048 + k * 1024); } while (0)
; #define PG8_WAIT_V(n) asm volatile("s_waitcnt vmcnt(" #n ")" ::: "memory")
; #define PG8_WAIT_L(n) asm volatile("s_waitcnt lgkmcnt(" #n ")" ::: "memory")
; #define PG8_BAR __builtin_amdgcn_s_barrier()
; #define PG8_SCHED __builtin_amdgcn_sched_barrier(0)
; template <class Epi, class Sched, bool ALIGN_EPI = false, bool SP2 = false>
; __device__ __forceinline__ void gemm_phase(PG8_LAS unsigned char* lds, const Gemm g, const Sched& S, const Epi& E) {
;     ...
;         const bool has_next = S.next(ui + 1, nxt);
;         const char* nA = has_next ? (const char*)g.A + (size_t)nxt.pm * tstep : cA; const char* nB = has_next ? (const char*)g.Bt + (size_t)nxt.pn * tstep : cB;
;         for (int t = 0; t < nt; t += 2) {
;             const bool last = (t == nt - 2);
;             const char* a1 = cA + (size_t)(t + 1) * kstep;
;             const char* a2 = last ? nA : cA + (size_t)(t + 2) * kstep; const char* b2 = last ? nB : cB + (size_t)(t + 2) * kstep;
;             const char* a3 = a2 + kstep; const char* b3 = b2 + kstep;
;             if (last && has_next) S.a_ready(nxt);
;             if constexpr (SP2) {
;             PG8_LDB(B0, 0, 0); PG8_LDB(B1, 0, 1); PG8_SCHED; PG8_LDA(At, 0, 0); PG8_STAGE(PG8_SA(1, 1), a1 + hstep, voffA);
;             PG8_WAIT_V(8); PG8_WAIT_L(0); PG8_BAR; PG8_MMA(0, 0, At, B0); PG8_MMA(0, 1, At, B1); PG8_BAR; PG8_SCHED;
;             PG8_LDA(At, 0, 1); PG8_STAGE(PG8_SB(0, 0), b2, voffB); PG8_STAGE(PG8_SB(0, 1), b2 + hstep, voffB); PG8_STAGE(PG8_SA(0, 0), a2, voffA);
;             PG8_WAIT_V(8); PG8_WAIT_L(0); PG8_BAR; PG8_MMA(1, 0, At, B0); PG8_MMA(1, 1, At, B1); PG8_BAR; PG8_SCHED;
.LBB0_599:
	s_add_u32 s10, s36, 0xfff80080
	s_addc_u32 s11, s37, -1
	s_add_i32 s55, 0, 0x10000
	s_cmp_eq_u32 s54, 28
	s_cselect_b32 s41, s19, s11
	s_cselect_b32 s40, s50, s10
	v_add_u32_e32 v140, s55, v143
	s_cselect_b32 s11, s17, s53
	s_cselect_b32 s10, s51, s52
	s_add_i32 s58, 0, 0x14000
	ds_read_b128 v[146:149], v140
	ds_read_b128 v[150:153], v140 offset:1024
	ds_read_b128 v[154:157], v140 offset:2048
	ds_read_b128 v[158:161], v140 offset:3072
	v_add_u32_e32 v140, s58, v143
	ds_read_b128 v[162:165], v140
	ds_read_b128 v[166:169], v140 offset:1024
	ds_read_b128 v[170:173], v140 offset:2048
	ds_read_b128 v[174:177], v140 offset:3072
	s_add_i32 m0, s7, 0xc000
	ds_read_b128 v[178:181], v145
	ds_read_b128 v[182:185], v145 offset:1024
	ds_read_b128 v[186:189], v145 offset:2048
	ds_read_b128 v[190:193], v145 offset:3072
	ds_read_b128 v[194:197], v145 offset:4096
	ds_read_b128 v[198:201], v145 offset:5120
	ds_read_b128 v[202:205], v145 offset:6144
	ds_read_b128 v[206:209], v145 offset:7168
	global_load_lds_dwordx4 v136, s[36:37]
	s_add_i32 m0, s7, 0xe000
	s_nop 0
	global_load_lds_dwordx4 v138, s[36:37]
	s_waitcnt vmcnt(8)
	s_waitcnt lgkmcnt(0)
	s_setprio 1
	s_barrier
	v_mfma_f32_16x16x32_bf16 v[126:129], v[146:149], v[178:181], v[126:129]
	v_mfma_f32_16x16x32_bf16 v[122:125], v[154:157], v[178:181], v[122:125]
	v_mfma_f32_16x16x32_bf16 v[118:121], v[146:149], v[186:189], v[118:121]
	v_mfma_f32_16x16x32_bf16 v[110:113], v[154:157], v[186:189], v[110:113]
	v_mfma_f32_16x16x32_bf16 v[102:105], v[146:149], v[194:197], v[102:105]
	v_mfma_f32_16x16x32_bf16 v[94:97], v[154:157], v[194:197], v[94:97]
	v_mfma_f32_16x16x32_bf16 v[86:89], v[146:149], v[202:205], v[86:89]
	v_mfma_f32_16x16x32_bf16 v[78:81], v[154:157], v[202:205], v[78:81]
	v_mfma_f32_16x16x32_bf16 v[126:129], v[150:153], v[182:185], v[126:129]
	v_mfma_f32_16x16x32_bf16 v[122:125], v[158:161], v[182:185], v[122:125]
	v_mfma_f32_16x16x32_bf16 v[118:121], v[150:153], v[190:193], v[118:121]
	v_mfma_f32_16x16x32_bf16 v[110:113], v[158:161], v[190:193], v[110:113]
	v_mfma_f32_16x16x32_bf16 v[102:105], v[150:153], v[198:201], v[102:105]
	v_mfma_f32_16x16x32_bf16 v[94:97], v[158:161], v[198:201], v[94:97]
	v_mfma_f32_16x16x32_bf16 v[86:89], v[150:153], v[206:209], v[86:89]
	v_mfma_f32_16x16x32_bf16 v[78:81], v[158:161], v[206:209], v[78:81]
	v_mfma_f32_16x16x32_bf16 v[114:117], v[162:165], v[178:181], v[114:117]
	v_mfma_f32_16x16x32_bf16 v[106:109], v[170:173], v[178:181], v[106:109]
	v_mfma_f32_16x16x32_bf16 v[98:101], v[162:165], v[186:189], v[98:101]
	v_mfma_f32_16x16x32_bf16 v[90:93], v[170:173], v[186:189], v[90:93]
	v_mfma_f32_16x16x32_bf16 v[82:85], v[162:165], v[194:197], v[82:85]
	v_mfma_f32_16x16x32_bf16 v[74:77], v[170:173], v[194:197], v[74:77]
	v_mfma_f32_16x16x32_bf16 v[70:73], v[162:165], v[202:205], v[70:73]
	v_mfma_f32_16x16x32_bf16 v[66:69], v[170:173], v[202:205], v[66:69]
	v_mfma_f32_16x16x32_bf16 v[114:117], v[166:169], v[182:185], v[114:117]
	v_mfma_f32_16x16x32_bf16 v[106:109], v[174:177], v[182:185], v[106:109]
	v_mfma_f32_16x16x32_bf16 v[98:101], v[166:169], v[190:193], v[98:101]
	v_mfma_f32_16x16x32_bf16 v[90:93], v[174:177], v[190:193], v[90:93]
	v_mfma_f32_16x16x32_bf16 v[82:85], v[166:169], v[198:201], v[82:85]
	v_mfma_f32_16x16x32_bf16 v[74:77], v[174:177], v[198:201], v[74:77]
	v_mfma_f32_16x16x32_bf16 v[70:73], v[166:169], v[206:209], v[70:73]
	v_mfma_f32_16x16x32_bf16 v[66:69], v[174:177], v[206:209], v[66:69]
	s_barrier
	s_setprio 0
	s_add_i32 s55, s55, s4
	s_add_u32 s100, s10, 0x80
	s_addc_u32 s101, s11, 0
	s_mov_b32 m0, s55
	ds_read_b128 v[178:181], v145 offset:16384
	ds_read_b128 v[182:185], v145 offset:17408
	ds_read_b128 v[186:189], v145 offset:18432
	ds_read_b128 v[190:193], v145 offset:19456
	ds_read_b128 v[194:197], v145 offset:20480
	ds_read_b128 v[198:201], v145 offset:21504
	ds_read_b128 v[202:205], v145 offset:22528
	ds_read_b128 v[206:209], v145 offset:23552
	global_load_lds_dwordx4 v0, s[10:11]
	s_add_i32 m0, s55, 0x2000
	s_add_u32 s56, s10, 0x80000
	s_addc_u32 s57, s11, 0
	s_add_i32 s55, s58, s4
	global_load_lds_dwordx4 v134, s[10:11]
	s_mov_b32 m0, s55
	s_add_u32 s98, s40, 0x80
	s_addc_u32 s99, s41, 0
	global_load_lds_dwordx4 v0, s[56:57]
	s_add_i32 m0, s55, 0x2000
	s_nop 0
	global_load_lds_dwordx4 v134, s[56:57]
	s_mov_b32 m0, s7
	s_nop 0
	global_load_lds_dwordx4 v130, s[40:41]
	s_mov_b32 m0, s21
	s_nop 0
	global_load_lds_dwordx4 v132, s[40:41]
	s_waitcnt vmcnt(8)
	s_waitcnt lgkmcnt(0)
	s_setprio 1
	s_barrier
	v_mfma_f32_16x16x32_bf16 v[62:65], v[146:149], v[178:181], v[62:65]
	v_mfma_f32_16x16x32_bf16 v[58:61], v[154:157], v[178:181], v[58:61]
	v_mfma_f32_16x16x32_bf16 v[54:57], v[146:149], v[186:189], v[54:57]
	v_mfma_f32_16x16x32_bf16 v[46:49], v[154:157], v[186:189], v[46:49]
	v_mfma_f32_16x16x32_bf16 v[38:41], v[146:149], v[194:197], v[38:41]
	v_mfma_f32_16x16x32_bf16 v[30:33], v[154:157], v[194:197], v[30:33]
	v_mfma_f32_16x16x32_bf16 v[22:25], v[146:149], v[202:205], v[22:25]
	v_mfma_f32_16x16x32_bf16 v[14:17], v[154:157], v[202:205], v[14:17]
	v_mfma_f32_16x16x32_bf16 v[62:65], v[150:153], v[182:185], v[62:65]
	v_mfma_f32_16x16x32_bf16 v[58:61], v[158:161], v[182:185], v[58:61]
	v_mfma_f32_16x16x32_bf16 v[54:57], v[150:153], v[190:193], v[54:57]
	v_mfma_f32_16x16x32_bf16 v[46:49], v[158:161], v[190:193], v[46:49]
	v_mfma_f32_16x16x32_bf16 v[38:41], v[150:153], v[198:201], v[38:41]
	v_mfma_f32_16x16x32_bf16 v[30:33], v[158:161], v[198:201], v[30:33]
	v_mfma_f32_16x16x32_bf16 v[22:25], v[150:153], v[206:209], v[22:25]
	v_mfma_f32_16x16x32_bf16 v[14:17], v[158:161], v[206:209], v[14:17]
	v_mfma_f32_16x16x32_bf16 v[50:53], v[162:165], v[178:181], v[50:53]
	v_mfma_f32_16x16x32_bf16 v[42:45], v[170:173], v[178:181], v[42:45]
	v_mfma_f32_16x16x32_bf16 v[34:37], v[162:165], v[186:189], v[34:37]
	v_mfma_f32_16x16x32_bf16 v[26:29], v[170:173], v[186:189], v[26:29]
	v_mfma_f32_16x16x32_bf16 v[18:21], v[162:165], v[194:197], v[18:21]
	v_mfma_f32_16x16x32_bf16 v[10:13], v[170:173], v[194:197], v[10:13]
	v_mfma_f32_16x16x32_bf16 v[6:9], v[162:165], v[202:205], v[6:9]
	v_mfma_f32_16x16x32_bf16 v[2:5], v[170:173], v[202:205], v[2:5]
	v_mfma_f32_16x16x32_bf16 v[50:53], v[166:169], v[182:185], v[50:53]
	v_mfma_f32_16x16x32_bf16 v[42:45], v[174:177], v[182:185], v[42:45]
	v_mfma_f32_16x16x32_bf16 v[34:37], v[166:169], v[190:193], v[34:37]
	v_mfma_f32_16x16x32_bf16 v[26:29], v[174:177], v[190:193], v[26:29]
	v_mfma_f32_16x16x32_bf16 v[18:21], v[166:169], v[198:201], v[18:21]
	v_mfma_f32_16x16x32_bf16 v[10:13], v[174:177], v[198:201], v[10:13]
	v_mfma_f32_16x16x32_bf16 v[6:9], v[166:169], v[206:209], v[6:9]
	v_mfma_f32_16x16x32_bf16 v[2:5], v[174:177], v[206:209], v[2:5]
	s_barrier
; #define PG8_STAGE(bufoff, gbase, voff) do { _Pragma("unroll") for (int _i = 0; _i < 2; ++_i) \
;         __builtin_amdgcn_global_load_lds((const unsigned*)((const char*)(gbase) + (voff)[_i]), (PG8_LAS unsigned*)(lds + (bufoff) + ldsw + _i * 8192), 16, 0, 0); } while (0)
; #define PG8_LDA(dst, b, h) do { _Pragma("unroll") for (int m = 0; m < 4; ++m) _Pragma("unroll") for (int k = 0; k < 2; ++k) dst[m][k] = *(const PG8_LAS bf16x8*)(lds + PG8_SA(b, h) + aoff + m * 2048 + k * 1024); } while (0)
; #define PG8_LDB(dst, b, h) do { _Pragma("unroll") for (int n = 0; n < 2; ++n) _Pragma("unroll") for (int k = 0; k < 2; ++k) dst[n][k] = *(const PG8_LAS bf16x8*)(lds + PG8_SB(b, h) + boff + n * 2048 + k * 1024); } while (0)
; #define PG8_MMA(ai, bj, At, Bt) do { __builtin_amdgcn_s_setprio(1); _Pragma("unroll") for (int m = 0; m < 4; ++m) _Pragma("unroll") for (int n = 0; n < 2; ++n) _Pragma("unroll") for (int k = 0; k < 2; ++k) \
;         acc[ai][bj][m][n] = __builtin_amdgcn_mfma_f32_16x16x32_bf16(Bt[n][k], At[m][k], acc[ai][bj][m][n], 0, 0, 0); __builtin_amdgcn_s_setprio(0); } while (0)
; #define PG8_WAIT_V(n) asm volatile("s_waitcnt vmcnt(" #n ")" ::: "memory")
; #define PG8_WAIT_L(n) asm volatile("s_waitcnt lgkmcnt(" #n ")" ::: "memory")
; #define PG8_BAR __builtin_amdgcn_s_barrier()
; #define PG8_SCHED __builtin_amdgcn_sched_barrier(0)
; template <class Epi, class Sched, bool ALIGN_EPI = false, bool SP2 = false>
; __device__ __forceinline__ void gemm_phase(PG8_LAS unsigned char* lds, const Gemm g, const Sched& S, const Epi& E) {
;     ...
;             PG8_WAIT_V(8); PG8_WAIT_L(0); PG8_BAR; PG8_MMA(1, 0, At, B0); PG8_MMA(1, 1, At, B1); PG8_BAR; PG8_SCHED;
;             PG8_LDB(B0, 1, 0); PG8_LDB(B1, 1, 1); PG8_SCHED; PG8_LDA(At, 1, 0); PG8_STAGE(PG8_SA(0, 1), a2 + hstep, voffA);
;             PG8_WAIT_V(8); PG8_WAIT_L(0); PG8_BAR; PG8_MMA(0, 0, At, B0); PG8_MMA(0, 1, At, B1); PG8_BAR; PG8_SCHED;
;             PG8_LDA(At, 1, 1); PG8_STAGE(PG8_SB(1, 0), b3, voffB); PG8_STAGE(PG8_SB(1, 1), b3 + hstep, voffB); PG8_STAGE(PG8_SA(1, 0), a3, voffA);
;             PG8_WAIT_V(8); PG8_WAIT_L(0); PG8_BAR; PG8_MMA(1, 0, At, B0); PG8_MMA(1, 1, At, B1); PG8_BAR; PG8_SCHED;
	s_setprio 0
	s_add_i32 s55, 0, 0x18000
	s_add_i32 s56, 0, 0x1c000
	v_add_u32_e32 v158, s55, v143
	v_add_u32_e32 v174, s56, v143
	ds_read_b128 v[146:149], v158
	ds_read_b128 v[150:153], v158 offset:1024
	ds_read_b128 v[154:157], v158 offset:2048
	ds_read_b128 v[158:161], v158 offset:3072
	ds_read_b128 v[162:165], v174
	ds_read_b128 v[166:169], v174 offset:1024
	ds_read_b128 v[170:173], v174 offset:2048
	ds_read_b128 v[174:177], v174 offset:3072
	s_add_u32 s40, s40, 0x80000
	s_addc_u32 s41, s41, 0
	s_mov_b32 m0, s30
	ds_read_b128 v[178:181], v145 offset:32768
	ds_read_b128 v[182:185], v145 offset:33792
	ds_read_b128 v[186:189], v145 offset:34816
	ds_read_b128 v[190:193], v145 offset:35840
	ds_read_b128 v[194:197], v145 offset:36864
	ds_read_b128 v[198:201], v145 offset:37888
	ds_read_b128 v[202:205], v145 offset:38912
	ds_read_b128 v[206:209], v145 offset:39936
	global_load_lds_dwordx4 v130, s[40:41]
	s_mov_b32 m0, s42
	s_nop 0
	global_load_lds_dwordx4 v132, s[40:41]
	s_waitcnt vmcnt(8)
	s_waitcnt lgkmcnt(0)
	s_setprio 1
	s_barrier
	v_mfma_f32_16x16x32_bf16 v[126:129], v[146:149], v[178:181], v[126:129]
	v_mfma_f32_16x16x32_bf16 v[122:125], v[154:157], v[178:181], v[122:125]
	v_mfma_f32_16x16x32_bf16 v[118:121], v[146:149], v[186:189], v[118:121]
	v_mfma_f32_16x16x32_bf16 v[110:113], v[154:157], v[186:189], v[110:113]
	v_mfma_f32_16x16x32_bf16 v[102:105], v[146:149], v[194:197], v[102:105]
	v_mfma_f32_16x16x32_bf16 v[94:97], v[154:157], v[194:197], v[94:97]
	v_mfma_f32_16x16x32_bf16 v[86:89], v[146:149], v[202:205], v[86:89]
	v_mfma_f32_16x16x32_bf16 v[78:81], v[154:157], v[202:205], v[78:81]
	v_mfma_f32_16x16x32_bf16 v[126:129], v[150:153], v[182:185], v[126:129]
	v_mfma_f32_16x16x32_bf16 v[122:125], v[158:161], v[182:185], v[122:125]
	v_mfma_f32_16x16x32_bf16 v[118:121], v[150:153], v[190:193], v[118:121]
	v_mfma_f32_16x16x32_bf16 v[110:113], v[158:161], v[190:193], v[110:113]
	v_mfma_f32_16x16x32_bf16 v[102:105], v[150:153], v[198:201], v[102:105]
	v_mfma_f32_16x16x32_bf16 v[94:97], v[158:161], v[198:201], v[94:97]
	v_mfma_f32_16x16x32_bf16 v[86:89], v[150:153], v[206:209], v[86:89]
	v_mfma_f32_16x16x32_bf16 v[78:81], v[158:161], v[206:209], v[78:81]
	v_mfma_f32_16x16x32_bf16 v[114:117], v[162:165], v[178:181], v[114:117]
	v_mfma_f32_16x16x32_bf16 v[106:109], v[170:173], v[178:181], v[106:109]
	v_mfma_f32_16x16x32_bf16 v[98:101], v[162:165], v[186:189], v[98:101]
	v_mfma_f32_16x16x32_bf16 v[90:93], v[170:173], v[186:189], v[90:93]
	v_mfma_f32_16x16x32_bf16 v[82:85], v[162:165], v[194:197], v[82:85]
	v_mfma_f32_16x16x32_bf16 v[74:77], v[170:173], v[194:197], v[74:77]
	v_mfma_f32_16x16x32_bf16 v[70:73], v[162:165], v[202:205], v[70:73]
	v_mfma_f32_16x16x32_bf16 v[66:69], v[170:173], v[202:205], v[66:69]
	v_mfma_f32_16x16x32_bf16 v[114:117], v[166:169], v[182:185], v[114:117]
	v_mfma_f32_16x16x32_bf16 v[106:109], v[174:177], v[182:185], v[106:109]
	v_mfma_f32_16x16x32_bf16 v[98:101], v[166:169], v[190:193], v[98:101]
	v_mfma_f32_16x16x32_bf16 v[90:93], v[174:177], v[190:193], v[90:93]
	v_mfma_f32_16x16x32_bf16 v[82:85], v[166:169], v[198:201], v[82:85]
	v_mfma_f32_16x16x32_bf16 v[74:77], v[174:177], v[198:201], v[74:77]
	v_mfma_f32_16x16x32_bf16 v[70:73], v[166:169], v[206:209], v[70:73]
	v_mfma_f32_16x16x32_bf16 v[66:69], v[174:177], v[206:209], v[66:69]
	s_barrier
	s_setprio 0
	s_add_i32 s40, s55, s4
	s_mov_b32 m0, s40
	ds_read_b128 v[178:181], v145 offset:49152
	ds_read_b128 v[182:185], v145 offset:50176
	ds_read_b128 v[186:189], v145 offset:51200
	ds_read_b128 v[190:193], v145 offset:52224
	ds_read_b128 v[194:197], v145 offset:53248
	ds_read_b128 v[198:201], v145 offset:54272
	ds_read_b128 v[202:205], v145 offset:55296
	ds_read_b128 v[206:209], v145 offset:56320
	global_load_lds_dwordx4 v0, s[100:101]
	s_add_i32 m0, s40, 0x2000
	s_add_i32 s40, s56, s4
	global_load_lds_dwordx4 v134, s[100:101]
	s_add_u32 s10, s10, 0x80080
	s_addc_u32 s11, s11, 0
	s_mov_b32 m0, s40
	s_nop 0
	global_load_lds_dwordx4 v0, s[10:11]
	s_add_i32 m0, s40, 0x2000
	s_nop 0
	global_load_lds_dwordx4 v134, s[10:11]
	s_mov_b32 m0, s43
	s_nop 0
	global_load_lds_dwordx4 v130, s[98:99]
	s_mov_b32 m0, s44
	s_nop 0
	global_load_lds_dwordx4 v132, s[98:99]
	s_waitcnt vmcnt(8)
	s_waitcnt lgkmcnt(0)
	s_setprio 1
	s_barrier
	v_mfma_f32_16x16x32_bf16 v[62:65], v[146:149], v[178:181], v[62:65]
	v_mfma_f32_16x16x32_bf16 v[58:61], v[154:157], v[178:181], v[58:61]
	v_mfma_f32_16x16x32_bf16 v[54:57], v[146:149], v[186:189], v[54:57]
	v_mfma_f32_16x16x32_bf16 v[46:49], v[154:157], v[186:189], v[46:49]
	v_mfma_f32_16x16x32_bf16 v[38:41], v[146:149], v[194:197], v[38:41]
	v_mfma_f32_16x16x32_bf16 v[30:33], v[154:157], v[194:197], v[30:33]
	v_mfma_f32_16x16x32_bf16 v[22:25], v[146:149], v[202:205], v[22:25]
	v_mfma_f32_16x16x32_bf16 v[14:17], v[154:157], v[202:205], v[14:17]
	v_mfma_f32_16x16x32_bf16 v[62:65], v[150:153], v[182:185], v[62:65]
	v_mfma_f32_16x16x32_bf16 v[58:61], v[158:161], v[182:185], v[58:61]
	v_mfma_f32_16x16x32_bf16 v[54:57], v[150:153], v[190:193], v[54:57]
	v_mfma_f32_16x16x32_bf16 v[46:49], v[158:161], v[190:193], v[46:49]
	v_mfma_f32_16x16x32_bf16 v[38:41], v[150:153], v[198:201], v[38:41]
	v_mfma_f32_16x16x32_bf16 v[30:33], v[158:161], v[198:201], v[30:33]
	v_mfma_f32_16x16x32_bf16 v[22:25], v[150:153], v[206:209], v[22:25]
	v_mfma_f32_16x16x32_bf16 v[14:17], v[158:161], v[206:209], v[14:17]
	v_mfma_f32_16x16x32_bf16 v[50:53], v[162:165], v[178:181], v[50:53]
	v_mfma_f32_16x16x32_bf16 v[42:45], v[170:173], v[178:181], v[42:45]
	v_mfma_f32_16x16x32_bf16 v[34:37], v[162:165], v[186:189], v[34:37]
	v_mfma_f32_16x16x32_bf16 v[26:29], v[170:173], v[186:189], v[26:29]
	v_mfma_f32_16x16x32_bf16 v[18:21], v[162:165], v[194:197], v[18:21]
	v_mfma_f32_16x16x32_bf16 v[10:13], v[170:173], v[194:197], v[10:13]
	v_mfma_f32_16x16x32_bf16 v[6:9], v[162:165], v[202:205], v[6:9]
	v_mfma_f32_16x16x32_bf16 v[2:5], v[170:173], v[202:205], v[2:5]
	v_mfma_f32_16x16x32_bf16 v[50:53], v[166:169], v[182:185], v[50:53]
	v_mfma_f32_16x16x32_bf16 v[42:45], v[174:177], v[182:185], v[42:45]
	v_mfma_f32_16x16x32_bf16 v[34:37], v[166:169], v[190:193], v[34:37]
	v_mfma_f32_16x16x32_bf16 v[26:29], v[174:177], v[190:193], v[26:29]
	v_mfma_f32_16x16x32_bf16 v[18:21], v[166:169], v[198:201], v[18:21]
	v_mfma_f32_16x16x32_bf16 v[10:13], v[174:177], v[198:201], v[10:13]
	v_mfma_f32_16x16x32_bf16 v[6:9], v[166:169], v[206:209], v[6:9]
	v_mfma_f32_16x16x32_bf16 v[2:5], v[174:177], v[206:209], v[2:5]
	s_barrier
	s_setprio 0
	s_add_i32 s54, s54, 2
	s_add_u32 s36, s36, 0x100
	s_addc_u32 s37, s37, 0
	s_add_u32 s52, s52, 0x100
	s_addc_u32 s53, s53, 0
	s_cmp_gt_u32 s54, 29
	s_cbranch_scc0 .LBB0_599
	s_and_b64 vcc, exec, s[12:13]
	s_cbranch_vccz .LBB0_602
	s_barrier
